# hgrn pass2: LDS-DMA staged loads + transposed-MFMA wide output stores + cvt_pk; in-proj epilogue hand-written for silu/sigmoid/copy tiles
# speedup vs baseline: 1.0053x; 1.0053x over previous
.LBB0_261:
	v_readfirstlane_b32 s55, v65
	s_and_b32 s18, s2, 7
	s_lshr_b32 s10, s3, 3
	s_ashr_i32 s54, s55, 6
	s_mul_i32 s100, s54, 0x1800
	s_cmp_ge_u32 s54, 6
	s_cbranch_scc0 .Lhg2_lo
	s_add_i32 s100, s100, 0x400
.Lhg2_lo:
	s_add_i32 s100, s100, 0x1ac00
	s_and_b32 s21, s3, 7
	s_cmp_eq_u32 s21, 0
	s_cbranch_scc1 .LBB0_267
	s_lshl_b32 s0, s10, 3
	s_ashr_i32 s1, s0, 31
	s_lshl_b64 s[4:5], s[0:1], 9
	s_and_b32 s24, s3, -8
	v_or_b32_e32 v112, s4, v104
	s_lshl_b32 s4, s54, 3
	s_ashr_i32 s25, s24, 31
	v_mov_b32_e32 v113, s5
	s_lshl_b64 s[0:1], s[0:1], 16
	s_ashr_i32 s5, s4, 31
	s_lshl_b64 s[36:37], s[24:25], 16
	v_readlane_b32 s19, v250, 17
	s_add_u32 s19, s19, s36
	v_readlane_b32 s20, v250, 18
	s_addc_u32 s20, s20, s37
	s_lshl_b64 s[4:5], s[4:5], 10
	s_add_u32 s36, s19, s4
	s_addc_u32 s37, s20, s5
	v_mov_b32_e32 v111, v64
	v_lshl_add_u64 v[0:1], s[36:37], 0, v[110:111]
	s_movk_i32 s19, 0x1000
	v_add_co_u32_e32 v0, vcc, s19, v0
	s_lshl_b64 s[24:25], s[24:25], 9
	s_nop 0
	v_addc_co_u32_e32 v1, vcc, 0, v1, vcc
	v_lshl_add_u64 v[2:3], v[102:103], 0, s[24:25]
	global_load_dword v133, v[0:1], off offset:3840
	global_load_dword v132, v[0:1], off offset:3584
	global_load_dword v115, v[0:1], off offset:3328
	global_load_dword v114, v[0:1], off offset:3072
	global_load_dwordx4 v[32:35], v[2:3], off offset:448
	global_load_dword v151, v[0:1], off offset:2816
	global_load_dword v150, v[0:1], off offset:2560
	global_load_dword v131, v[0:1], off offset:2304
	global_load_dword v130, v[0:1], off offset:2048
	global_load_dwordx4 v[40:43], v[2:3], off offset:384
	global_load_dword v149, v[0:1], off offset:1792
	global_load_dword v148, v[0:1], off offset:1536
	global_load_dword v129, v[0:1], off offset:1280
	global_load_dword v128, v[0:1], off offset:1024
	global_load_dwordx4 v[36:39], v[2:3], off offset:320
	global_load_dword v147, v[0:1], off offset:768
	global_load_dword v146, v[0:1], off offset:512
	global_load_dword v125, v[0:1], off offset:256
	global_load_dword v124, v[0:1], off
	global_load_dwordx4 v[48:51], v[2:3], off offset:256
	global_load_dword v145, v110, s[36:37] offset:3840
	global_load_dword v144, v110, s[36:37] offset:3584
	global_load_dword v123, v110, s[36:37] offset:3328
	global_load_dword v122, v110, s[36:37] offset:3072
	global_load_dwordx4 v[44:47], v[2:3], off offset:192
	global_load_dword v143, v110, s[36:37] offset:2816
	global_load_dword v142, v110, s[36:37] offset:2560
	global_load_dword v121, v110, s[36:37] offset:2304
	global_load_dword v120, v110, s[36:37] offset:2048
	global_load_dwordx4 v[52:55], v[2:3], off offset:128
	global_load_dword v135, v110, s[36:37] offset:1792
	global_load_dword v134, v110, s[36:37] offset:1536
	global_load_dword v119, v110, s[36:37] offset:1280
	global_load_dword v118, v110, s[36:37] offset:1024
	global_load_dwordx4 v[56:59], v[2:3], off offset:64
	global_load_dword v137, v110, s[36:37] offset:768
	global_load_dword v136, v110, s[36:37] offset:512
	global_load_dword v127, v110, s[36:37] offset:256
	global_load_dword v126, v110, s[36:37]
	global_load_dwordx4 v[60:63], v[2:3], off
	s_add_u32 s0, s4, s0
	s_addc_u32 s1, s5, s1
	v_mov_b32_e32 v24, 0
	s_mov_b32 s19, 0
	v_mov_b32_e32 v117, s1
	v_or_b32_e32 v116, s0, v108
	v_mov_b32_e32 v25, v24
	v_mov_b32_e32 v26, v24
	v_mov_b32_e32 v27, v24
	v_mov_b32_e32 v16, v24
	v_mov_b32_e32 v17, v24
	v_mov_b32_e32 v18, v24
	v_mov_b32_e32 v19, v24
	v_mov_b32_e32 v8, v24
	v_mov_b32_e32 v9, v24
	v_mov_b32_e32 v10, v24
	v_mov_b32_e32 v11, v24
	v_mov_b32_e32 v4, v24
	v_mov_b32_e32 v5, v24
	v_mov_b32_e32 v6, v24
	v_mov_b32_e32 v7, v24
	v_mov_b32_e32 v28, v24
	v_mov_b32_e32 v29, v24
	v_mov_b32_e32 v30, v24
	v_mov_b32_e32 v31, v24
	v_mov_b32_e32 v20, v24
	v_mov_b32_e32 v21, v24
	v_mov_b32_e32 v22, v24
	v_mov_b32_e32 v23, v24
	v_mov_b32_e32 v12, v24
	v_mov_b32_e32 v13, v24
	v_mov_b32_e32 v14, v24
	v_mov_b32_e32 v15, v24
	v_mov_b32_e32 v0, v24
	v_mov_b32_e32 v1, v24
	v_mov_b32_e32 v2, v24
	v_mov_b32_e32 v3, v24
	s_waitcnt vmcnt(0)
	v_mov_b64_e32 v[96:97], v[34:35]
	v_mov_b64_e32 v[94:95], v[32:33]
	s_waitcnt vmcnt(30)
	v_mov_b64_e32 v[92:93], v[42:43]
	v_mov_b64_e32 v[90:91], v[40:41]
	s_waitcnt vmcnt(25)
	v_mov_b64_e32 v[88:89], v[38:39]
	v_mov_b64_e32 v[86:87], v[36:37]
	s_waitcnt vmcnt(20)
	v_mov_b64_e32 v[84:85], v[50:51]
	v_mov_b64_e32 v[82:83], v[48:49]
	s_waitcnt vmcnt(15)
	v_mov_b64_e32 v[80:81], v[46:47]
	v_mov_b64_e32 v[78:79], v[44:45]
	s_waitcnt vmcnt(10)
	v_mov_b64_e32 v[76:77], v[54:55]
	v_mov_b64_e32 v[74:75], v[52:53]
	s_waitcnt vmcnt(5)
	v_mov_b64_e32 v[72:73], v[58:59]
	v_mov_b64_e32 v[70:71], v[56:57]
	s_waitcnt vmcnt(0)
	v_mov_b64_e32 v[68:69], v[62:63]
	v_mov_b64_e32 v[66:67], v[60:61]

.LBB0_268:
	s_lshl_b32 s18, s18, 10
	s_and_b32 s10, s10, 1
	s_ashr_i32 s0, s3, 7
	s_xor_b32 s19, s18, 0x1f80
	s_ashr_i32 s1, s0, 31
	s_lshl_b32 s4, s10, 25
	v_readlane_b32 s5, v250, 42
	s_add_u32 s20, s5, s4
	v_readlane_b32 s4, v250, 43
	s_addc_u32 s24, s4, 0
	s_lshl_b64 s[4:5], s[0:1], 24
	s_add_u32 s20, s20, s4
	s_addc_u32 s33, s24, s5
	v_readlane_b32 s0, v250, 44
	s_add_u32 s0, s0, s4
	v_readlane_b32 s1, v250, 45
	s_addc_u32 s1, s1, s5
	s_lshl_b32 s24, s3, 4
	s_and_b32 s36, s24, 0x700
	s_add_u32 s29, s0, s36
	s_addc_u32 s24, s1, 0
	s_cmp_eq_u32 s10, 0
	s_cselect_b64 s[48:49], -1, 0
	s_and_b64 s[0:1], s[48:49], exec
	s_cselect_b32 s1, s8, s76
	s_cselect_b32 s0, s9, s28
	s_add_u32 s37, s1, s4
	s_addc_u32 s50, s0, s5
	s_lshl_b32 s0, s54, 4
	s_ashr_i32 s1, s0, 31
	s_add_u32 s51, s80, s4
	s_addc_u32 s52, s81, s5
	s_add_u32 s25, s20, s36
	s_addc_u32 s10, s33, 0
	s_and_b64 s[4:5], s[48:49], exec
	s_cselect_b32 s56, 0x800, s78
	s_add_u32 s20, s37, s36
	s_addc_u32 s33, s50, 0
	s_lshl_b64 s[4:5], s[0:1], 1
	s_add_u32 s4, s20, s4
	s_addc_u32 s5, s33, s5
	s_add_u32 s33, s51, s36
	s_addc_u32 s20, s52, 0
	s_lshl_b32 s1, s21, 10
	v_cndmask_b32_e64 v32, v105, v99, s[48:49]
	s_xor_b32 s21, s1, 0x1fc0
	s_waitcnt vmcnt(0)
	v_lshl_or_b32 v66, v32, 11, v152
	s_and_b64 s[36:37], s[48:49], exec
	s_cselect_b32 s1, s1, s21
	v_add_u32_e32 v68, s56, v66
	s_lshl_b32 s1, s1, 11
	s_waitcnt vmcnt(38)
	v_add_u32_e32 v70, s56, v68
	s_add_u32 s36, s33, s1
	v_add_u32_e32 v72, s56, v70
	s_addc_u32 s37, s20, 0
	s_waitcnt vmcnt(29)
	v_add_u32_e32 v74, s56, v72
	s_add_u32 s50, s25, s1
	v_add_u32_e32 v76, s56, v74
	s_addc_u32 s51, s10, 0
	s_waitcnt vmcnt(28)
	v_add_u32_e32 v78, s56, v76
	s_add_u32 s52, s29, s1
	v_add_u32_e32 v80, s56, v78
	s_addc_u32 s53, s24, 0
	s_waitcnt vmcnt(19)
	v_add_u32_e32 v82, s56, v80
	v_add_u32_e32 v84, s56, v82
	s_waitcnt vmcnt(26)
	v_add_u32_e32 v86, s56, v84
	v_add_u32_e32 v88, s56, v86
	s_waitcnt vmcnt(20)
	v_add_u32_e32 v90, s56, v88
	v_add_u32_e32 v92, s56, v90
	s_waitcnt vmcnt(22)
	v_add_u32_e32 v94, s56, v92
	v_add_u32_e32 v96, s56, v94
	v_mbcnt_lo_u32_b32 v246, -1, 0
	v_mbcnt_hi_u32_b32 v246, -1, v246
	v_and_b32_e32 v247, 7, v246
	v_lshrrev_b32_e32 v248, 3, v246
	v_lshlrev_b32_e32 v247, 4, v247
	v_lshlrev_b32_e32 v249, 1, v246
	v_sub_u32_e32 v247, v247, v249
	v_mul_lo_u32 v248, v248, s56
	v_add3_u32 v244, v66, v247, v248
	v_lshl_add_u32 v245, s56, 3, v244
	v_lshl_add_u32 v246, v246, 1, s100
	s_add_i32 m0, s100, 0
	s_nop 0
	global_load_lds_dwordx4 v244, s[50:51]
	s_add_i32 m0, s100, 1024
	s_nop 0
	global_load_lds_dwordx4 v245, s[50:51]
	s_add_i32 m0, s100, 2048
	s_nop 0
	global_load_lds_dwordx4 v244, s[52:53]
	s_add_i32 m0, s100, 3072
	s_nop 0
	global_load_lds_dwordx4 v245, s[52:53]
	s_add_i32 m0, s100, 4096
	s_nop 0
	global_load_lds_dwordx4 v244, s[36:37]
	s_add_i32 m0, s100, 5120
	s_nop 0
	global_load_lds_dwordx4 v245, s[36:37]
	s_ashr_i32 s50, s55, 7
	s_lshl_b32 s1, s54, 1
	s_and_b32 s51, s1, 2
	s_lshl_b32 s1, s50, 4
	v_lshlrev_b32_e32 v32, 1, v98
	v_mov_b32_e32 v33, v64
	s_cmp_gt_u32 s50, 1
	v_lshl_add_u64 v[112:113], s[4:5], 0, v[32:33]
	v_add_u32_e32 v238, s18, v98
	v_sub_u32_e32 v239, s19, v98
	v_add_u32_e32 v239, 0x7f, v239
	v_cndmask_b32_e64 v238, v239, v238, s[48:49]
	v_lshlrev_b32_e32 v238, 11, v238
	v_lshl_add_u32 v238, v109, 1, v238
	v_mov_b32_e32 v239, 0
	v_lshl_add_u64 v[228:229], s[4:5], 0, v[238:239]
	v_mov_b32_e32 v238, 0x8000
	v_mov_b32_e32 v240, 0xffff8000
	v_cndmask_b32_e64 v238, v240, v238, s[48:49]
	v_cndmask_b32_e64 v239, -1, 0, s[48:49]
	v_lshl_add_u64 v[230:231], v[228:229], 0, v[238:239]
	v_lshl_add_u64 v[232:233], v[230:231], 0, v[238:239]
	v_lshl_add_u64 v[234:235], v[232:233], 0, v[238:239]
	v_lshlrev_b32_e32 v236, 2, v238
	v_mov_b32_e32 v237, v239
	s_cselect_b64 s[4:5], -1, 0
	s_cmp_le_i32 s51, s50
	s_movk_i32 s53, 0x110
	s_movk_i32 s52, 0x90
	v_or_b32_e32 v114, s18, v109
	s_mov_b32 s21, 0
	v_mov_b32_e32 v67, v64
	v_mov_b32_e32 v69, v64
	v_mov_b32_e32 v71, v64
	v_mov_b32_e32 v73, v64
	v_mov_b32_e32 v75, v64
	v_mov_b32_e32 v77, v64
	v_mov_b32_e32 v79, v64
	v_mov_b32_e32 v81, v64
	v_mov_b32_e32 v83, v64
	v_mov_b32_e32 v85, v64
	v_mov_b32_e32 v87, v64
	v_mov_b32_e32 v89, v64
	v_mov_b32_e32 v91, v64
	v_mov_b32_e32 v93, v64
	v_mov_b32_e32 v95, v64
	v_mov_b32_e32 v97, v64
	v_or_b32_e32 v40, s1, v109
	v_or_b32_e32 v41, s1, v98
	v_or_b32_e32 v42, s0, v98
	s_cselect_b64 s[0:1], -1, 0
	s_cmp_eq_u32 s51, 0
	s_cselect_b64 s[36:37], -1, 0
	s_and_b64 s[4:5], s[4:5], s[36:37]
	s_and_b64 s[4:5], s[4:5], exec
	s_mov_b32 s4, 0xcc00
	s_cselect_b32 s4, s4, 0x4400
	s_add_i32 s4, s4, 0
	s_lshl_b32 s5, s51, 4
	v_or_b32_e32 v43, s5, v98
	v_mov_b32_e32 v44, s4
	v_or_b32_e32 v47, 1, v40
	v_or_b32_e32 v48, 2, v40
	v_or_b32_e32 v49, 3, v40
	v_or_b32_e32 v50, s5, v107
	v_readlane_b32 s4, v255, 4
	v_mul_lo_u32 v41, v41, s53
	v_mul_lo_u32 v42, v42, s52
	v_mad_u32_u24 v45, v43, s53, v44
	v_mul_lo_u32 v46, v40, s52
	s_cmp_lt_i32 s51, s50
	v_mad_u32_u24 v44, v50, s53, v44
	v_lshl_add_u32 v51, v43, 1, s4
	v_cmp_gt_i32_e64 s[50:51], v43, v40
	v_cmp_gt_i32_e64 s[52:53], v43, v47
	v_cmp_gt_i32_e64 s[54:55], v43, v48
	v_cmp_gt_i32_e64 s[56:57], v43, v49
	v_lshl_add_u32 v43, v50, 1, s4
	s_cselect_b64 s[36:37], -1, 0
	v_cmp_gt_i32_e64 s[58:59], v50, v40
	v_cmp_gt_i32_e64 s[60:61], v50, v47
	v_cmp_gt_i32_e64 s[62:63], v50, v48
	v_cmp_gt_i32_e64 s[64:65], v50, v49
	v_add_u32_e32 v122, v45, v104
	v_add_u32_e32 v123, v51, v46
	v_add_u32_e32 v124, v44, v104
	v_add_u32_e32 v126, v43, v46
	v_add_u32_e32 v127, v155, v42
	v_add_u32_e32 v128, v156, v41
	s_waitcnt vmcnt(0)
	s_branch .LBB0_270
.LBB0_269:
	v_cvt_pk_bf16_f32 v48, v24, v25
	v_cvt_pk_bf16_f32 v49, v26, v27
	v_cvt_pk_bf16_f32 v50, v16, v17
	v_cvt_pk_bf16_f32 v51, v18, v19
	v_cvt_pk_bf16_f32 v52, v8, v9
	v_cvt_pk_bf16_f32 v53, v10, v11
	v_cvt_pk_bf16_f32 v54, v4, v5
	v_cvt_pk_bf16_f32 v55, v6, v7
	v_cvt_pk_bf16_f32 v56, v28, v29
	v_cvt_pk_bf16_f32 v57, v30, v31
	v_cvt_pk_bf16_f32 v58, v20, v21
	v_cvt_pk_bf16_f32 v59, v22, v23
	v_cndmask_b32_e64 v40, v40, 0, s[58:59]
	v_bfe_u32 v44, v40, 16, 1
	v_add3_u32 v40, v40, v44, s6
	v_cvt_pk_bf16_f32 v60, v12, v13
	ds_write_b16_d16_hi v126, v40
	v_cndmask_b32_e64 v40, v41, 0, s[60:61]
	v_bfe_u32 v41, v40, 16, 1
	v_add3_u32 v40, v40, v41, s6
	v_cvt_pk_bf16_f32 v61, v14, v15
	ds_write_b16_d16_hi v126, v40 offset:144
	v_cndmask_b32_e64 v40, v42, 0, s[62:63]
	v_bfe_u32 v41, v40, 16, 1
	v_add3_u32 v40, v40, v41, s6
	v_cvt_pk_bf16_f32 v62, v0, v1
	ds_write_b16_d16_hi v126, v40 offset:288
	v_cndmask_b32_e64 v40, v43, 0, s[64:65]
	v_bfe_u32 v41, v40, 16, 1
	v_add3_u32 v40, v40, v41, s6
	v_cvt_pk_bf16_f32 v63, v2, v3
	v_add_u32_e32 v138, 0x8800, v163
	ds_write_b16_d16_hi v126, v40 offset:432
	s_waitcnt lgkmcnt(0)
	s_barrier
	ds_read_b128 v[44:47], v127
	ds_read_b128 v[40:43], v127 offset:64
	ds_read_b128 v[172:175], v162
	ds_read_b128 v[184:187], v162 offset:64
	ds_read2_b64 v[188:191], v138 offset1:4
	ds_read2_b64 v[192:195], v138 offset0:8 offset1:12
	ds_read2_b64 v[196:199], v138 offset0:16 offset1:20
	ds_read2_b64 v[200:203], v138 offset0:24 offset1:28
	s_waitcnt lgkmcnt(5)
	v_mfma_f32_16x16x32_bf16 v[172:175], v[44:47], v[172:175], 0
	s_waitcnt lgkmcnt(4)
	v_mfma_f32_16x16x32_bf16 v[172:175], v[40:43], v[184:187], v[172:175]
	s_waitcnt lgkmcnt(3)
	v_mfma_f32_16x16x32_bf16 v[172:175], v[48:51], v[188:191], v[172:175]
	s_waitcnt lgkmcnt(2)
	v_mfma_f32_16x16x32_bf16 v[172:175], v[52:55], v[192:195], v[172:175]
	s_waitcnt lgkmcnt(1)
	v_mfma_f32_16x16x32_bf16 v[172:175], v[56:59], v[196:199], v[172:175]
	s_waitcnt lgkmcnt(0)
	v_mfma_f32_16x16x32_bf16 v[172:175], v[60:63], v[200:203], v[172:175]
	s_nop 7
	v_cvt_pk_bf16_f32 v240, v172, v173
	v_cvt_pk_bf16_f32 v241, v174, v175
	global_store_dwordx2 v[228:229], v[240:241], off
	v_add_u32_e32 v182, 0x9800, v163
	ds_read_b128 v[172:175], v162 offset:2304
	ds_read_b128 v[184:187], v162 offset:2368
	ds_read2_b64 v[188:191], v182 offset0:32 offset1:36
	ds_read2_b64 v[192:195], v182 offset0:40 offset1:44
	ds_read2_b64 v[196:199], v182 offset0:48 offset1:52
	ds_read2_b64 v[200:203], v182 offset0:56 offset1:60
	s_waitcnt lgkmcnt(5)
	v_mfma_f32_16x16x32_bf16 v[172:175], v[44:47], v[172:175], 0
	s_waitcnt lgkmcnt(4)
	v_mfma_f32_16x16x32_bf16 v[172:175], v[40:43], v[184:187], v[172:175]
	s_waitcnt lgkmcnt(3)
	v_mfma_f32_16x16x32_bf16 v[172:175], v[48:51], v[188:191], v[172:175]
	s_waitcnt lgkmcnt(2)
	v_mfma_f32_16x16x32_bf16 v[172:175], v[52:55], v[192:195], v[172:175]
	s_waitcnt lgkmcnt(1)
	v_mfma_f32_16x16x32_bf16 v[172:175], v[56:59], v[196:199], v[172:175]
	s_waitcnt lgkmcnt(0)
	v_mfma_f32_16x16x32_bf16 v[172:175], v[60:63], v[200:203], v[172:175]
	s_nop 7
	v_cvt_pk_bf16_f32 v242, v172, v173
	v_cvt_pk_bf16_f32 v243, v174, v175
	global_store_dwordx2 v[230:231], v[242:243], off
	v_add_u32_e32 v182, 0xa800, v163
	ds_read_b128 v[172:175], v162 offset:4608
	ds_read_b128 v[184:187], v162 offset:4672
	ds_read2_b64 v[188:191], v182 offset0:64 offset1:68
	ds_read2_b64 v[192:195], v182 offset0:72 offset1:76
	ds_read2_b64 v[196:199], v182 offset0:80 offset1:84
	ds_read2_b64 v[200:203], v182 offset0:88 offset1:92
	s_waitcnt lgkmcnt(5)
	v_mfma_f32_16x16x32_bf16 v[172:175], v[44:47], v[172:175], 0
	s_waitcnt lgkmcnt(4)
	v_mfma_f32_16x16x32_bf16 v[172:175], v[40:43], v[184:187], v[172:175]
	s_waitcnt lgkmcnt(3)
	v_mfma_f32_16x16x32_bf16 v[172:175], v[48:51], v[188:191], v[172:175]
	s_waitcnt lgkmcnt(2)
	v_mfma_f32_16x16x32_bf16 v[172:175], v[52:55], v[192:195], v[172:175]
	s_waitcnt lgkmcnt(1)
	v_mfma_f32_16x16x32_bf16 v[172:175], v[56:59], v[196:199], v[172:175]
	s_waitcnt lgkmcnt(0)
	v_mfma_f32_16x16x32_bf16 v[172:175], v[60:63], v[200:203], v[172:175]
	s_nop 7
	v_cvt_pk_bf16_f32 v240, v172, v173
	v_cvt_pk_bf16_f32 v241, v174, v175
	global_store_dwordx2 v[232:233], v[240:241], off
	v_add_u32_e32 v182, 0xb800, v163
	ds_read_b128 v[172:175], v162 offset:6912
	ds_read_b128 v[184:187], v162 offset:6976
	ds_read2_b64 v[188:191], v182 offset0:96 offset1:100
	ds_read2_b64 v[192:195], v182 offset0:104 offset1:108
	ds_read2_b64 v[196:199], v182 offset0:112 offset1:116
	ds_read2_b64 v[200:203], v182 offset0:120 offset1:124
	s_waitcnt lgkmcnt(5)
	v_mfma_f32_16x16x32_bf16 v[172:175], v[44:47], v[172:175], 0
	s_waitcnt lgkmcnt(4)
	v_mfma_f32_16x16x32_bf16 v[172:175], v[40:43], v[184:187], v[172:175]
	s_waitcnt lgkmcnt(3)
	v_mfma_f32_16x16x32_bf16 v[48:51], v[48:51], v[188:191], v[172:175]
	s_waitcnt lgkmcnt(2)
	v_mfma_f32_16x16x32_bf16 v[48:51], v[52:55], v[192:195], v[48:51]
	s_waitcnt lgkmcnt(1)
	v_mfma_f32_16x16x32_bf16 v[48:51], v[56:59], v[196:199], v[48:51]
	s_waitcnt lgkmcnt(0)
	v_mfma_f32_16x16x32_bf16 v[48:51], v[60:63], v[200:203], v[48:51]
	s_nop 7
	v_cvt_pk_bf16_f32 v242, v48, v49
	v_cvt_pk_bf16_f32 v243, v50, v51
	global_store_dwordx2 v[234:235], v[242:243], off
	v_add_u32_e32 v138, s16, v100
	v_add_u32_e32 v139, v156, v157
	ds_read_b128 v[48:51], v138
	ds_read_b128 v[52:55], v139 offset:60928
	ds_read_b128 v[56:59], v139 offset:60992
	ds_read_b128 v[60:63], v165
	ds_read_b128 v[172:175], v139 offset:63232
	ds_read_b128 v[184:187], v139 offset:63296
	ds_read_b128 v[188:191], v166
	ds_read_b128 v[192:195], v164 offset:60928
	ds_read_b128 v[196:199], v164 offset:60992
	ds_read_b128 v[200:203], v167
	ds_read_b128 v[204:207], v164 offset:63232
	ds_read_b128 v[208:211], v164 offset:63296
	s_waitcnt lgkmcnt(11)
	v_pk_mul_f32 v[24:25], v[24:25], v[48:49]
	v_pk_mul_f32 v[26:27], v[26:27], v[50:51]
	s_waitcnt lgkmcnt(8)
	v_pk_mul_f32 v[16:17], v[16:17], v[60:61]
	v_pk_mul_f32 v[18:19], v[18:19], v[62:63]
	s_waitcnt lgkmcnt(5)
	v_pk_mul_f32 v[8:9], v[8:9], v[188:189]
	v_pk_mul_f32 v[10:11], v[10:11], v[190:191]
	s_waitcnt lgkmcnt(2)
	v_pk_mul_f32 v[4:5], v[4:5], v[200:201]
	v_pk_mul_f32 v[6:7], v[6:7], v[202:203]
	v_mfma_f32_16x16x32_bf16 v[24:27], v[52:55], v[44:47], v[24:27]
	v_mfma_f32_16x16x32_bf16 v[16:19], v[172:175], v[44:47], v[16:19]
	v_mfma_f32_16x16x32_bf16 v[8:11], v[192:195], v[44:47], v[8:11]
	s_waitcnt lgkmcnt(1)
	v_mfma_f32_16x16x32_bf16 v[4:7], v[204:207], v[44:47], v[4:7]
	v_mfma_f32_16x16x32_bf16 v[24:27], v[56:59], v[40:43], v[24:27]
	v_mfma_f32_16x16x32_bf16 v[16:19], v[184:187], v[40:43], v[16:19]
	v_mfma_f32_16x16x32_bf16 v[8:11], v[196:199], v[40:43], v[8:11]
	s_waitcnt lgkmcnt(0)
	v_mfma_f32_16x16x32_bf16 v[4:7], v[208:211], v[40:43], v[4:7]
	ds_read_b128 v[48:51], v158 offset:9216
	ds_read_b128 v[52:55], v158 offset:9280
	ds_read_b128 v[56:59], v138 offset:256
	ds_read_b128 v[60:63], v138 offset:320
	ds_read_b128 v[172:175], v158 offset:11520
	ds_read_b128 v[184:187], v158 offset:11584
	ds_read_b128 v[188:191], v158 offset:13824
	ds_read_b128 v[192:195], v158 offset:13888
	ds_read_b128 v[196:199], v138 offset:384
	ds_read_b128 v[200:203], v138 offset:448
	ds_read_b128 v[204:207], v158 offset:16128
	ds_read_b128 v[208:211], v158 offset:16192
	s_waitcnt lgkmcnt(9)
	v_pk_mul_f32 v[28:29], v[28:29], v[56:57]
	v_pk_mul_f32 v[30:31], v[30:31], v[58:59]
	s_waitcnt lgkmcnt(8)
	v_pk_mul_f32 v[20:21], v[20:21], v[60:61]
	v_pk_mul_f32 v[22:23], v[22:23], v[62:63]
	s_waitcnt lgkmcnt(3)
	v_pk_mul_f32 v[12:13], v[12:13], v[196:197]
	v_pk_mul_f32 v[14:15], v[14:15], v[198:199]
	s_waitcnt lgkmcnt(2)
	v_pk_mul_f32 v[0:1], v[0:1], v[200:201]
	v_pk_mul_f32 v[2:3], v[2:3], v[202:203]
	v_mfma_f32_16x16x32_bf16 v[28:31], v[48:51], v[44:47], v[28:31]
	v_mfma_f32_16x16x32_bf16 v[20:23], v[172:175], v[44:47], v[20:23]
	v_mfma_f32_16x16x32_bf16 v[12:15], v[188:191], v[44:47], v[12:15]
	s_waitcnt lgkmcnt(1)
	v_mfma_f32_16x16x32_bf16 v[0:3], v[204:207], v[44:47], v[0:3]
	v_mfma_f32_16x16x32_bf16 v[28:31], v[52:55], v[40:43], v[28:31]
	v_mfma_f32_16x16x32_bf16 v[20:23], v[184:187], v[40:43], v[20:23]
	v_mfma_f32_16x16x32_bf16 v[12:15], v[192:195], v[40:43], v[12:15]
	s_waitcnt lgkmcnt(0)
	v_mfma_f32_16x16x32_bf16 v[0:3], v[208:211], v[40:43], v[0:3]
	v_lshl_add_u64 v[228:229], v[228:229], 0, v[236:237]
	v_lshl_add_u64 v[230:231], v[230:231], 0, v[236:237]
	v_lshl_add_u64 v[232:233], v[232:233], 0, v[236:237]
	v_lshl_add_u64 v[234:235], v[234:235], 0, v[236:237]
	s_add_i32 s21, s21, 64
	s_sub_i32 s19, s19, 64
	s_cmpk_lg_i32 s21, 0x400
	s_barrier
	s_cbranch_scc0 .LBB0_260
.LBB0_270:
	s_waitcnt vmcnt(4)
	ds_read_u16 v111, v246
	ds_read_u16 v116, v246 offset:128
	ds_read_u16 v118, v246 offset:256
	ds_read_u16 v120, v246 offset:384
	ds_read_u16 v125, v246 offset:512
	ds_read_u16 v130, v246 offset:640
	ds_read_u16 v132, v246 offset:768
	ds_read_u16 v134, v246 offset:896
	ds_read_u16 v135, v246 offset:1024
	ds_read_u16 v142, v246 offset:1152
	ds_read_u16 v144, v246 offset:1280
	ds_read_u16 v146, v246 offset:1408
	ds_read_u16 v148, v246 offset:1536
	ds_read_u16 v150, v246 offset:1664
	ds_read_u16 v168, v246 offset:1792
	ds_read_u16 v170, v246 offset:1920
	ds_read_u16 v212, v246 offset:2048
	ds_read_u16 v213, v246 offset:2176
	ds_read_u16 v214, v246 offset:2304
	ds_read_u16 v215, v246 offset:2432
	ds_read_u16 v216, v246 offset:2560
	ds_read_u16 v217, v246 offset:2688
	ds_read_u16 v218, v246 offset:2816
	ds_read_u16 v219, v246 offset:2944
	ds_read_u16 v220, v246 offset:3072
	ds_read_u16 v221, v246 offset:3200
	ds_read_u16 v222, v246 offset:3328
	ds_read_u16 v223, v246 offset:3456
	ds_read_u16 v224, v246 offset:3584
	ds_read_u16 v225, v246 offset:3712
	ds_read_u16 v226, v246 offset:3840
	ds_read_u16 v227, v246 offset:3968
	ds_read_u16 v115, v246 offset:4096
	ds_read_u16 v117, v246 offset:4224
	ds_read_u16 v119, v246 offset:4352
	ds_read_u16 v121, v246 offset:4480
	ds_read_u16 v129, v246 offset:4608
	ds_read_u16 v131, v246 offset:4736
	ds_read_u16 v133, v246 offset:4864
	ds_read_u16 v137, v246 offset:4992
	ds_read_u16 v136, v246 offset:5120
	ds_read_u16 v143, v246 offset:5248
	ds_read_u16 v145, v246 offset:5376
	ds_read_u16 v147, v246 offset:5504
	ds_read_u16 v149, v246 offset:5632
	ds_read_u16 v151, v246 offset:5760
	ds_read_u16 v169, v246 offset:5888
	ds_read_u16 v171, v246 offset:6016
	s_waitcnt lgkmcnt(15)
	v_lshlrev_b32_e32 v55, 16, v111
	v_add_f32_e32 v52, 0, v55
	v_lshlrev_b32_e32 v193, 16, v116
	v_add_f32_e32 v194, v52, v193
	v_lshlrev_b32_e32 v189, 16, v118
	v_add_f32_e32 v192, v194, v189
	v_lshlrev_b32_e32 v190, 16, v120
	v_add_f32_e32 v191, v192, v190
	v_lshlrev_b32_e32 v185, 16, v125
	v_add_f32_e32 v188, v191, v185
	v_lshlrev_b32_e32 v186, 16, v130
	v_add_f32_e32 v187, v188, v186
	v_lshlrev_b32_e32 v173, 16, v132
	v_add_f32_e32 v184, v187, v173
	v_lshlrev_b32_e32 v174, 16, v134
	v_add_f32_e32 v175, v184, v174
	v_lshlrev_b32_e32 v44, 16, v135
	v_add_f32_e32 v172, v175, v44
	v_lshlrev_b32_e32 v62, 16, v142
	v_add_f32_e32 v63, v172, v62
	v_lshlrev_b32_e32 v45, 16, v144
	v_add_f32_e32 v61, v63, v45
	v_lshlrev_b32_e32 v59, 16, v146
	v_add_f32_e32 v60, v61, v59
	v_lshlrev_b32_e32 v46, 16, v148
	v_add_f32_e32 v58, v60, v46
	v_lshlrev_b32_e32 v56, 16, v150
	v_add_f32_e32 v57, v58, v56
	v_lshlrev_b32_e32 v47, 16, v168
	v_add_f32_e32 v54, v57, v47
	v_lshlrev_b32_e32 v48, 16, v170
	v_add_f32_e32 v50, v54, v48
	ds_write_b32 v101, v50
	v_lshl_or_b32 v32, v213, 16, v212
	v_lshl_or_b32 v33, v215, 16, v214
	v_lshl_or_b32 v34, v217, 16, v216
	v_lshl_or_b32 v35, v219, 16, v218
	v_lshl_or_b32 v36, v221, 16, v220
	v_lshl_or_b32 v37, v223, 16, v222
	v_lshl_or_b32 v38, v225, 16, v224
	v_lshl_or_b32 v39, v227, 16, v226
	ds_write_b128 v160, v[32:35]
	ds_write_b128 v160, v[36:39] offset:16
	s_waitcnt lgkmcnt(0)
	s_barrier
	ds_read2st64_b32 v[42:43], v153 offset1:2
	ds_read2st64_b32 v[40:41], v153 offset0:4 offset1:6
	s_cmpk_eq_i32 s21, 0x3c0
	s_cbranch_scc1 .Lhg2_nopf
	s_add_i32 s4, s18, s21
	s_add_i32 s70, s4, 64
	s_and_b64 s[4:5], s[48:49], exec
	s_cselect_b32 s4, s70, s19
	s_ashr_i32 s5, s4, 31
	s_lshl_b64 s[70:71], s[4:5], 11
	s_add_u32 vcc_lo, s33, s70
	s_addc_u32 vcc_hi, s20, s71
	s_add_u32 s4, s25, s70
	s_addc_u32 s5, s10, s71
	s_add_u32 s70, s29, s70
	s_addc_u32 s71, s24, s71
	s_add_i32 m0, s100, 0
	s_nop 0
	global_load_lds_dwordx4 v244, s[4:5]
	s_add_i32 m0, s100, 1024
	s_nop 0
	global_load_lds_dwordx4 v245, s[4:5]
	s_add_i32 m0, s100, 2048
	s_nop 0
	global_load_lds_dwordx4 v244, s[70:71]
	s_add_i32 m0, s100, 3072
	s_nop 0
	global_load_lds_dwordx4 v245, s[70:71]
	s_add_i32 m0, s100, 4096
	s_nop 0
	global_load_lds_dwordx4 v244, vcc
	s_add_i32 m0, s100, 5120
	s_nop 0
	global_load_lds_dwordx4 v245, vcc

.LBB0_584:
	v_readlane_b32 s0, v250, 25
	v_mbcnt_lo_u32_b32 v130, -1, 0
	v_mbcnt_hi_u32_b32 v130, -1, v130
	s_nop 1
	s_lshr_b32 s1, s0, 8
	s_bfe_u32 s0, s0, 0x20006
	v_and_b32_e32 v131, 15, v130
	v_lshrrev_b32_e32 v132, 4, v130
	s_lshr_b32 s4, s2, 1
	s_mov_b32 s37, 0
	s_cmp_lt_u32 s4, 2
	s_cbranch_scc1 .Lepi_ty
	s_mov_b32 s37, 1
	s_cmp_lt_u32 s4, 6
	s_cbranch_scc1 .Lepi_ty
	s_mov_b32 s37, 2
	s_cmp_lt_u32 s4, 8
	s_cbranch_scc1 .Lepi_ty
	s_mov_b32 s37, 0
	s_cmp_lt_u32 s4, 10
	s_cbranch_scc1 .Lepi_ty
	s_mov_b32 s37, 3
	s_cmp_gt_u32 s4, 18
	s_cbranch_scc1 .Lepi_ty
	s_sub_u32 s4, s4, 10
	s_mul_i32 s5, s4, 11
	s_lshr_b32 s5, s5, 5
	s_mul_i32 s5, s5, 3
	s_sub_u32 s4, s4, s5
	s_mov_b32 s37, 4
	s_cmp_eq_u32 s4, 0
	s_cbranch_scc1 .Lepi_ty
	s_mov_b32 s37, 5
	s_cmp_eq_u32 s4, 1
	s_cbranch_scc1 .Lepi_ty
	s_mov_b32 s37, 2
.Lepi_ty:
	s_cmp_eq_u32 s37, 1
	s_cbranch_scc1 .Lepi_old
	s_cmp_eq_u32 s37, 4
	s_cbranch_scc1 .Lepi_old
	s_cmp_eq_u32 s37, 5
	s_cbranch_scc1 .Lepi_old
	s_lshl_b32 s4, s2, 8
	s_cmp_lt_u32 s4, 0x1400
	s_cbranch_scc0 .Lepi_tB
	s_lshr_b32 s5, s4, 10
	s_lshl_b32 s5, s5, 25
	s_and_b32 s4, s4, 0x3ff
	s_mov_b32 s10, 11
	s_branch .Lepi_tD
.Lepi_tB:
	s_cmp_lt_u32 s4, 0x2600
	s_cbranch_scc0 .Lepi_tC
	s_sub_u32 s4, s4, 0x1400
	s_lshr_b32 s5, s4, 9
	s_lshl_b32 s5, s5, 24
	s_add_u32 s5, s5, 0xa000000
	s_and_b32 s4, s4, 0x1ff
	s_mov_b32 s10, 10
	s_branch .Lepi_tD
.Lepi_tC:
	s_sub_u32 s4, s4, 0x2600
	s_lshr_b32 s5, s4, 10
	s_lshl_b32 s5, s5, 25
	s_add_u32 s5, s5, 0x13000000
	s_and_b32 s4, s4, 0x3ff
	s_mov_b32 s10, 11
.Lepi_tD:
	s_lshl_b32 s4, s4, 1
	s_add_u32 s5, s5, s4
	s_add_u32 s8, s90, 0x7000000
	s_addc_u32 s9, s91, 0
	s_add_u32 s8, s8, s5
	s_addc_u32 s9, s9, 0
	s_lshl_b32 s20, 16, s10
	s_mul_i32 s36, s20, 5
	s_lshl_b32 s18, s3, 8
	s_lshl_b32 s19, s1, 6
	s_add_u32 s18, s18, s19
	v_add_u32_e32 v157, s18, v131
	v_lshlrev_b32_e32 v157, s10, v157
	v_lshl_add_u32 v157, v132, 4, v157
	s_lshl_b32 s19, s0, 6
	v_add_u32_e32 v157, s19, v157
	v_mov_b32_e32 v167, v157
	s_mov_b32 s56, 0xbfb8aa3b
	s_mov_b32 s57, 0xbfb8aa3b
	s_mov_b32 s58, 1.0
	s_mov_b32 s59, 1.0
	s_cmp_eq_u32 s37, 0
	s_cbranch_scc1 .Lepi_silu
	s_cmp_eq_u32 s37, 1
	s_cbranch_scc1 .Lepi_log
	s_cmp_eq_u32 s37, 3
	s_cbranch_scc1 .Lepi_sig
	s_cmp_eq_u32 s37, 2
	s_cbranch_scc1 .Lepi_copy
	s_branch .Lepi_old
.Lepi_silu:
	v_pk_mul_f32 v[158:159], v[126:127], s[56:57]
	v_pk_mul_f32 v[160:161], v[128:129], s[56:57]
	v_pk_mul_f32 v[162:163], v[122:123], s[56:57]
	v_pk_mul_f32 v[164:165], v[124:125], s[56:57]
	v_exp_f32_e32 v158, v158
	v_exp_f32_e32 v159, v159
	v_exp_f32_e32 v160, v160
	v_exp_f32_e32 v161, v161
	v_exp_f32_e32 v162, v162
	v_exp_f32_e32 v163, v163
	v_exp_f32_e32 v164, v164
	v_exp_f32_e32 v165, v165
	v_pk_add_f32 v[158:159], v[158:159], s[58:59]
	v_pk_add_f32 v[160:161], v[160:161], s[58:59]
	v_pk_add_f32 v[162:163], v[162:163], s[58:59]
	v_pk_add_f32 v[164:165], v[164:165], s[58:59]
	v_rcp_f32_e32 v158, v158
	v_rcp_f32_e32 v159, v159
	v_rcp_f32_e32 v160, v160
	v_rcp_f32_e32 v161, v161
	v_rcp_f32_e32 v162, v162
	v_rcp_f32_e32 v163, v163
	v_rcp_f32_e32 v164, v164
	v_rcp_f32_e32 v165, v165
	v_pk_mul_f32 v[126:127], v[126:127], v[158:159]
	v_pk_mul_f32 v[128:129], v[128:129], v[160:161]
	v_pk_mul_f32 v[122:123], v[122:123], v[162:163]
	v_pk_mul_f32 v[124:125], v[124:125], v[164:165]
	v_cvt_pk_bf16_f32 v126, v126, v127
	v_cvt_pk_bf16_f32 v127, v128, v129
	v_cvt_pk_bf16_f32 v128, v122, v123
	v_cvt_pk_bf16_f32 v129, v124, v125
	global_store_dwordx4 v157, v[126:129], s[8:9]
	v_pk_mul_f32 v[158:159], v[118:119], s[56:57]
	v_pk_mul_f32 v[160:161], v[120:121], s[56:57]
	v_pk_mul_f32 v[162:163], v[114:115], s[56:57]
	v_pk_mul_f32 v[164:165], v[116:117], s[56:57]
	v_exp_f32_e32 v158, v158
	v_exp_f32_e32 v159, v159
	v_exp_f32_e32 v160, v160
	v_exp_f32_e32 v161, v161
	v_exp_f32_e32 v162, v162
	v_exp_f32_e32 v163, v163
	v_exp_f32_e32 v164, v164
	v_exp_f32_e32 v165, v165
	v_pk_add_f32 v[158:159], v[158:159], s[58:59]
	v_pk_add_f32 v[160:161], v[160:161], s[58:59]
	v_pk_add_f32 v[162:163], v[162:163], s[58:59]
	v_pk_add_f32 v[164:165], v[164:165], s[58:59]
	v_rcp_f32_e32 v158, v158
	v_rcp_f32_e32 v159, v159
	v_rcp_f32_e32 v160, v160
	v_rcp_f32_e32 v161, v161
	v_rcp_f32_e32 v162, v162
	v_rcp_f32_e32 v163, v163
	v_rcp_f32_e32 v164, v164
	v_rcp_f32_e32 v165, v165
	v_pk_mul_f32 v[118:119], v[118:119], v[158:159]
	v_pk_mul_f32 v[120:121], v[120:121], v[160:161]
	v_pk_mul_f32 v[114:115], v[114:115], v[162:163]
	v_pk_mul_f32 v[116:117], v[116:117], v[164:165]
	v_cvt_pk_bf16_f32 v118, v118, v119
	v_cvt_pk_bf16_f32 v119, v120, v121
	v_cvt_pk_bf16_f32 v120, v114, v115
	v_cvt_pk_bf16_f32 v121, v116, v117
	global_store_dwordx4 v157, v[118:121], s[8:9] offset:256
	v_add_u32_e32 v157, s20, v157
	v_pk_mul_f32 v[158:159], v[110:111], s[56:57]
	v_pk_mul_f32 v[160:161], v[112:113], s[56:57]
	v_pk_mul_f32 v[162:163], v[106:107], s[56:57]
	v_pk_mul_f32 v[164:165], v[108:109], s[56:57]
	v_exp_f32_e32 v158, v158
	v_exp_f32_e32 v159, v159
	v_exp_f32_e32 v160, v160
	v_exp_f32_e32 v161, v161
	v_exp_f32_e32 v162, v162
	v_exp_f32_e32 v163, v163
	v_exp_f32_e32 v164, v164
	v_exp_f32_e32 v165, v165
	v_pk_add_f32 v[158:159], v[158:159], s[58:59]
	v_pk_add_f32 v[160:161], v[160:161], s[58:59]
	v_pk_add_f32 v[162:163], v[162:163], s[58:59]
	v_pk_add_f32 v[164:165], v[164:165], s[58:59]
	v_rcp_f32_e32 v158, v158
	v_rcp_f32_e32 v159, v159
	v_rcp_f32_e32 v160, v160
	v_rcp_f32_e32 v161, v161
	v_rcp_f32_e32 v162, v162
	v_rcp_f32_e32 v163, v163
	v_rcp_f32_e32 v164, v164
	v_rcp_f32_e32 v165, v165
	v_pk_mul_f32 v[110:111], v[110:111], v[158:159]
	v_pk_mul_f32 v[112:113], v[112:113], v[160:161]
	v_pk_mul_f32 v[106:107], v[106:107], v[162:163]
	v_pk_mul_f32 v[108:109], v[108:109], v[164:165]
	v_cvt_pk_bf16_f32 v110, v110, v111
	v_cvt_pk_bf16_f32 v111, v112, v113
	v_cvt_pk_bf16_f32 v112, v106, v107
	v_cvt_pk_bf16_f32 v113, v108, v109
	global_store_dwordx4 v157, v[110:113], s[8:9]
	v_pk_mul_f32 v[158:159], v[102:103], s[56:57]
	v_pk_mul_f32 v[160:161], v[104:105], s[56:57]
	v_pk_mul_f32 v[162:163], v[98:99], s[56:57]
	v_pk_mul_f32 v[164:165], v[100:101], s[56:57]
	v_exp_f32_e32 v158, v158
	v_exp_f32_e32 v159, v159
	v_exp_f32_e32 v160, v160
	v_exp_f32_e32 v161, v161
	v_exp_f32_e32 v162, v162
	v_exp_f32_e32 v163, v163
	v_exp_f32_e32 v164, v164
	v_exp_f32_e32 v165, v165
	v_pk_add_f32 v[158:159], v[158:159], s[58:59]
	v_pk_add_f32 v[160:161], v[160:161], s[58:59]
	v_pk_add_f32 v[162:163], v[162:163], s[58:59]
	v_pk_add_f32 v[164:165], v[164:165], s[58:59]
	v_rcp_f32_e32 v158, v158
	v_rcp_f32_e32 v159, v159
	v_rcp_f32_e32 v160, v160
	v_rcp_f32_e32 v161, v161
	v_rcp_f32_e32 v162, v162
	v_rcp_f32_e32 v163, v163
	v_rcp_f32_e32 v164, v164
	v_rcp_f32_e32 v165, v165
	v_pk_mul_f32 v[102:103], v[102:103], v[158:159]
	v_pk_mul_f32 v[104:105], v[104:105], v[160:161]
	v_pk_mul_f32 v[98:99], v[98:99], v[162:163]
	v_pk_mul_f32 v[100:101], v[100:101], v[164:165]
	v_cvt_pk_bf16_f32 v102, v102, v103
	v_cvt_pk_bf16_f32 v103, v104, v105
	v_cvt_pk_bf16_f32 v104, v98, v99
	v_cvt_pk_bf16_f32 v105, v100, v101
	global_store_dwordx4 v157, v[102:105], s[8:9] offset:256
	v_add_u32_e32 v157, s20, v157
	v_pk_mul_f32 v[158:159], v[94:95], s[56:57]
	v_pk_mul_f32 v[160:161], v[96:97], s[56:57]
	v_pk_mul_f32 v[162:163], v[90:91], s[56:57]
	v_pk_mul_f32 v[164:165], v[92:93], s[56:57]
	v_exp_f32_e32 v158, v158
	v_exp_f32_e32 v159, v159
	v_exp_f32_e32 v160, v160
	v_exp_f32_e32 v161, v161
	v_exp_f32_e32 v162, v162
	v_exp_f32_e32 v163, v163
	v_exp_f32_e32 v164, v164
	v_exp_f32_e32 v165, v165
	v_pk_add_f32 v[158:159], v[158:159], s[58:59]
	v_pk_add_f32 v[160:161], v[160:161], s[58:59]
	v_pk_add_f32 v[162:163], v[162:163], s[58:59]
	v_pk_add_f32 v[164:165], v[164:165], s[58:59]
	v_rcp_f32_e32 v158, v158
	v_rcp_f32_e32 v159, v159
	v_rcp_f32_e32 v160, v160
	v_rcp_f32_e32 v161, v161
	v_rcp_f32_e32 v162, v162
	v_rcp_f32_e32 v163, v163
	v_rcp_f32_e32 v164, v164
	v_rcp_f32_e32 v165, v165
	v_pk_mul_f32 v[94:95], v[94:95], v[158:159]
	v_pk_mul_f32 v[96:97], v[96:97], v[160:161]
	v_pk_mul_f32 v[90:91], v[90:91], v[162:163]
	v_pk_mul_f32 v[92:93], v[92:93], v[164:165]
	v_cvt_pk_bf16_f32 v94, v94, v95
	v_cvt_pk_bf16_f32 v95, v96, v97
	v_cvt_pk_bf16_f32 v96, v90, v91
	v_cvt_pk_bf16_f32 v97, v92, v93
	global_store_dwordx4 v157, v[94:97], s[8:9]
	v_pk_mul_f32 v[158:159], v[86:87], s[56:57]
	v_pk_mul_f32 v[160:161], v[88:89], s[56:57]
	v_pk_mul_f32 v[162:163], v[82:83], s[56:57]
	v_pk_mul_f32 v[164:165], v[84:85], s[56:57]
	v_exp_f32_e32 v158, v158
	v_exp_f32_e32 v159, v159
	v_exp_f32_e32 v160, v160
	v_exp_f32_e32 v161, v161
	v_exp_f32_e32 v162, v162
	v_exp_f32_e32 v163, v163
	v_exp_f32_e32 v164, v164
	v_exp_f32_e32 v165, v165
	v_pk_add_f32 v[158:159], v[158:159], s[58:59]
	v_pk_add_f32 v[160:161], v[160:161], s[58:59]
	v_pk_add_f32 v[162:163], v[162:163], s[58:59]
	v_pk_add_f32 v[164:165], v[164:165], s[58:59]
	v_rcp_f32_e32 v158, v158
	v_rcp_f32_e32 v159, v159
	v_rcp_f32_e32 v160, v160
	v_rcp_f32_e32 v161, v161
	v_rcp_f32_e32 v162, v162
	v_rcp_f32_e32 v163, v163
	v_rcp_f32_e32 v164, v164
	v_rcp_f32_e32 v165, v165
	v_pk_mul_f32 v[86:87], v[86:87], v[158:159]
	v_pk_mul_f32 v[88:89], v[88:89], v[160:161]
	v_pk_mul_f32 v[82:83], v[82:83], v[162:163]
	v_pk_mul_f32 v[84:85], v[84:85], v[164:165]
	v_cvt_pk_bf16_f32 v86, v86, v87
	v_cvt_pk_bf16_f32 v87, v88, v89
	v_cvt_pk_bf16_f32 v88, v82, v83
	v_cvt_pk_bf16_f32 v89, v84, v85
	global_store_dwordx4 v157, v[86:89], s[8:9] offset:256
	v_add_u32_e32 v157, s20, v157
	v_pk_mul_f32 v[158:159], v[78:79], s[56:57]
	v_pk_mul_f32 v[160:161], v[80:81], s[56:57]
	v_pk_mul_f32 v[162:163], v[74:75], s[56:57]
	v_pk_mul_f32 v[164:165], v[76:77], s[56:57]
	v_exp_f32_e32 v158, v158
	v_exp_f32_e32 v159, v159
	v_exp_f32_e32 v160, v160
	v_exp_f32_e32 v161, v161
	v_exp_f32_e32 v162, v162
	v_exp_f32_e32 v163, v163
	v_exp_f32_e32 v164, v164
	v_exp_f32_e32 v165, v165
	v_pk_add_f32 v[158:159], v[158:159], s[58:59]
	v_pk_add_f32 v[160:161], v[160:161], s[58:59]
	v_pk_add_f32 v[162:163], v[162:163], s[58:59]
	v_pk_add_f32 v[164:165], v[164:165], s[58:59]
	v_rcp_f32_e32 v158, v158
	v_rcp_f32_e32 v159, v159
	v_rcp_f32_e32 v160, v160
	v_rcp_f32_e32 v161, v161
	v_rcp_f32_e32 v162, v162
	v_rcp_f32_e32 v163, v163
	v_rcp_f32_e32 v164, v164
	v_rcp_f32_e32 v165, v165
	v_pk_mul_f32 v[78:79], v[78:79], v[158:159]
	v_pk_mul_f32 v[80:81], v[80:81], v[160:161]
	v_pk_mul_f32 v[74:75], v[74:75], v[162:163]
	v_pk_mul_f32 v[76:77], v[76:77], v[164:165]
	v_cvt_pk_bf16_f32 v78, v78, v79
	v_cvt_pk_bf16_f32 v79, v80, v81
	v_cvt_pk_bf16_f32 v80, v74, v75
	v_cvt_pk_bf16_f32 v81, v76, v77
	global_store_dwordx4 v157, v[78:81], s[8:9]
	v_pk_mul_f32 v[158:159], v[70:71], s[56:57]
	v_pk_mul_f32 v[160:161], v[72:73], s[56:57]
	v_pk_mul_f32 v[162:163], v[66:67], s[56:57]
	v_pk_mul_f32 v[164:165], v[68:69], s[56:57]
	v_exp_f32_e32 v158, v158
	v_exp_f32_e32 v159, v159
	v_exp_f32_e32 v160, v160
	v_exp_f32_e32 v161, v161
	v_exp_f32_e32 v162, v162
	v_exp_f32_e32 v163, v163
	v_exp_f32_e32 v164, v164
	v_exp_f32_e32 v165, v165
	v_pk_add_f32 v[158:159], v[158:159], s[58:59]
	v_pk_add_f32 v[160:161], v[160:161], s[58:59]
	v_pk_add_f32 v[162:163], v[162:163], s[58:59]
	v_pk_add_f32 v[164:165], v[164:165], s[58:59]
	v_rcp_f32_e32 v158, v158
	v_rcp_f32_e32 v159, v159
	v_rcp_f32_e32 v160, v160
	v_rcp_f32_e32 v161, v161
	v_rcp_f32_e32 v162, v162
	v_rcp_f32_e32 v163, v163
	v_rcp_f32_e32 v164, v164
	v_rcp_f32_e32 v165, v165
	v_pk_mul_f32 v[70:71], v[70:71], v[158:159]
	v_pk_mul_f32 v[72:73], v[72:73], v[160:161]
	v_pk_mul_f32 v[66:67], v[66:67], v[162:163]
	v_pk_mul_f32 v[68:69], v[68:69], v[164:165]
	v_cvt_pk_bf16_f32 v70, v70, v71
	v_cvt_pk_bf16_f32 v71, v72, v73
	v_cvt_pk_bf16_f32 v72, v66, v67
	v_cvt_pk_bf16_f32 v73, v68, v69
	global_store_dwordx4 v157, v[70:73], s[8:9] offset:256
	v_add_u32_e32 v157, s36, v157
	v_pk_mul_f32 v[158:159], v[60:61], s[56:57]
	v_pk_mul_f32 v[160:161], v[62:63], s[56:57]
	v_pk_mul_f32 v[162:163], v[56:57], s[56:57]
	v_pk_mul_f32 v[164:165], v[58:59], s[56:57]
	v_exp_f32_e32 v158, v158
	v_exp_f32_e32 v159, v159
	v_exp_f32_e32 v160, v160
	v_exp_f32_e32 v161, v161
	v_exp_f32_e32 v162, v162
	v_exp_f32_e32 v163, v163
	v_exp_f32_e32 v164, v164
	v_exp_f32_e32 v165, v165
	v_pk_add_f32 v[158:159], v[158:159], s[58:59]
	v_pk_add_f32 v[160:161], v[160:161], s[58:59]
	v_pk_add_f32 v[162:163], v[162:163], s[58:59]
	v_pk_add_f32 v[164:165], v[164:165], s[58:59]
	v_rcp_f32_e32 v158, v158
	v_rcp_f32_e32 v159, v159
	v_rcp_f32_e32 v160, v160
	v_rcp_f32_e32 v161, v161
	v_rcp_f32_e32 v162, v162
	v_rcp_f32_e32 v163, v163
	v_rcp_f32_e32 v164, v164
	v_rcp_f32_e32 v165, v165
	v_pk_mul_f32 v[60:61], v[60:61], v[158:159]
	v_pk_mul_f32 v[62:63], v[62:63], v[160:161]
	v_pk_mul_f32 v[56:57], v[56:57], v[162:163]
	v_pk_mul_f32 v[58:59], v[58:59], v[164:165]
	v_cvt_pk_bf16_f32 v60, v60, v61
	v_cvt_pk_bf16_f32 v61, v62, v63
	v_cvt_pk_bf16_f32 v62, v56, v57
	v_cvt_pk_bf16_f32 v63, v58, v59
	global_store_dwordx4 v157, v[60:63], s[8:9]
	v_pk_mul_f32 v[158:159], v[52:53], s[56:57]
	v_pk_mul_f32 v[160:161], v[54:55], s[56:57]
	v_pk_mul_f32 v[162:163], v[48:49], s[56:57]
	v_pk_mul_f32 v[164:165], v[50:51], s[56:57]
	v_exp_f32_e32 v158, v158
	v_exp_f32_e32 v159, v159
	v_exp_f32_e32 v160, v160
	v_exp_f32_e32 v161, v161
	v_exp_f32_e32 v162, v162
	v_exp_f32_e32 v163, v163
	v_exp_f32_e32 v164, v164
	v_exp_f32_e32 v165, v165
	v_pk_add_f32 v[158:159], v[158:159], s[58:59]
	v_pk_add_f32 v[160:161], v[160:161], s[58:59]
	v_pk_add_f32 v[162:163], v[162:163], s[58:59]
	v_pk_add_f32 v[164:165], v[164:165], s[58:59]
	v_rcp_f32_e32 v158, v158
	v_rcp_f32_e32 v159, v159
	v_rcp_f32_e32 v160, v160
	v_rcp_f32_e32 v161, v161
	v_rcp_f32_e32 v162, v162
	v_rcp_f32_e32 v163, v163
	v_rcp_f32_e32 v164, v164
	v_rcp_f32_e32 v165, v165
	v_pk_mul_f32 v[52:53], v[52:53], v[158:159]
	v_pk_mul_f32 v[54:55], v[54:55], v[160:161]
	v_pk_mul_f32 v[48:49], v[48:49], v[162:163]
	v_pk_mul_f32 v[50:51], v[50:51], v[164:165]
	v_cvt_pk_bf16_f32 v52, v52, v53
	v_cvt_pk_bf16_f32 v53, v54, v55
	v_cvt_pk_bf16_f32 v54, v48, v49
	v_cvt_pk_bf16_f32 v55, v50, v51
	global_store_dwordx4 v157, v[52:55], s[8:9] offset:256
	v_add_u32_e32 v157, s20, v157
	v_pk_mul_f32 v[158:159], v[44:45], s[56:57]
	v_pk_mul_f32 v[160:161], v[46:47], s[56:57]
	v_pk_mul_f32 v[162:163], v[40:41], s[56:57]
	v_pk_mul_f32 v[164:165], v[42:43], s[56:57]
	v_exp_f32_e32 v158, v158
	v_exp_f32_e32 v159, v159
	v_exp_f32_e32 v160, v160
	v_exp_f32_e32 v161, v161
	v_exp_f32_e32 v162, v162
	v_exp_f32_e32 v163, v163
	v_exp_f32_e32 v164, v164
	v_exp_f32_e32 v165, v165
	v_pk_add_f32 v[158:159], v[158:159], s[58:59]
	v_pk_add_f32 v[160:161], v[160:161], s[58:59]
	v_pk_add_f32 v[162:163], v[162:163], s[58:59]
	v_pk_add_f32 v[164:165], v[164:165], s[58:59]
	v_rcp_f32_e32 v158, v158
	v_rcp_f32_e32 v159, v159
	v_rcp_f32_e32 v160, v160
	v_rcp_f32_e32 v161, v161
	v_rcp_f32_e32 v162, v162
	v_rcp_f32_e32 v163, v163
	v_rcp_f32_e32 v164, v164
	v_rcp_f32_e32 v165, v165
	v_pk_mul_f32 v[44:45], v[44:45], v[158:159]
	v_pk_mul_f32 v[46:47], v[46:47], v[160:161]
	v_pk_mul_f32 v[40:41], v[40:41], v[162:163]
	v_pk_mul_f32 v[42:43], v[42:43], v[164:165]
	v_cvt_pk_bf16_f32 v44, v44, v45
	v_cvt_pk_bf16_f32 v45, v46, v47
	v_cvt_pk_bf16_f32 v46, v40, v41
	v_cvt_pk_bf16_f32 v47, v42, v43
	global_store_dwordx4 v157, v[44:47], s[8:9]
	v_pk_mul_f32 v[158:159], v[36:37], s[56:57]
	v_pk_mul_f32 v[160:161], v[38:39], s[56:57]
	v_pk_mul_f32 v[162:163], v[32:33], s[56:57]
	v_pk_mul_f32 v[164:165], v[34:35], s[56:57]
	v_exp_f32_e32 v158, v158
	v_exp_f32_e32 v159, v159
	v_exp_f32_e32 v160, v160
	v_exp_f32_e32 v161, v161
	v_exp_f32_e32 v162, v162
	v_exp_f32_e32 v163, v163
	v_exp_f32_e32 v164, v164
	v_exp_f32_e32 v165, v165
	v_pk_add_f32 v[158:159], v[158:159], s[58:59]
	v_pk_add_f32 v[160:161], v[160:161], s[58:59]
	v_pk_add_f32 v[162:163], v[162:163], s[58:59]
	v_pk_add_f32 v[164:165], v[164:165], s[58:59]
	v_rcp_f32_e32 v158, v158
	v_rcp_f32_e32 v159, v159
	v_rcp_f32_e32 v160, v160
	v_rcp_f32_e32 v161, v161
	v_rcp_f32_e32 v162, v162
	v_rcp_f32_e32 v163, v163
	v_rcp_f32_e32 v164, v164
	v_rcp_f32_e32 v165, v165
	v_pk_mul_f32 v[36:37], v[36:37], v[158:159]
	v_pk_mul_f32 v[38:39], v[38:39], v[160:161]
	v_pk_mul_f32 v[32:33], v[32:33], v[162:163]
	v_pk_mul_f32 v[34:35], v[34:35], v[164:165]
	v_cvt_pk_bf16_f32 v36, v36, v37
	v_cvt_pk_bf16_f32 v37, v38, v39
	v_cvt_pk_bf16_f32 v38, v32, v33
	v_cvt_pk_bf16_f32 v39, v34, v35
	global_store_dwordx4 v157, v[36:39], s[8:9] offset:256
	v_add_u32_e32 v157, s20, v157
	v_pk_mul_f32 v[158:159], v[28:29], s[56:57]
	v_pk_mul_f32 v[160:161], v[30:31], s[56:57]
	v_pk_mul_f32 v[162:163], v[24:25], s[56:57]
	v_pk_mul_f32 v[164:165], v[26:27], s[56:57]
	v_exp_f32_e32 v158, v158
	v_exp_f32_e32 v159, v159
	v_exp_f32_e32 v160, v160
	v_exp_f32_e32 v161, v161
	v_exp_f32_e32 v162, v162
	v_exp_f32_e32 v163, v163
	v_exp_f32_e32 v164, v164
	v_exp_f32_e32 v165, v165
	v_pk_add_f32 v[158:159], v[158:159], s[58:59]
	v_pk_add_f32 v[160:161], v[160:161], s[58:59]
	v_pk_add_f32 v[162:163], v[162:163], s[58:59]
	v_pk_add_f32 v[164:165], v[164:165], s[58:59]
	v_rcp_f32_e32 v158, v158
	v_rcp_f32_e32 v159, v159
	v_rcp_f32_e32 v160, v160
	v_rcp_f32_e32 v161, v161
	v_rcp_f32_e32 v162, v162
	v_rcp_f32_e32 v163, v163
	v_rcp_f32_e32 v164, v164
	v_rcp_f32_e32 v165, v165
	v_pk_mul_f32 v[28:29], v[28:29], v[158:159]
	v_pk_mul_f32 v[30:31], v[30:31], v[160:161]
	v_pk_mul_f32 v[24:25], v[24:25], v[162:163]
	v_pk_mul_f32 v[26:27], v[26:27], v[164:165]
	v_cvt_pk_bf16_f32 v28, v28, v29
	v_cvt_pk_bf16_f32 v29, v30, v31
	v_cvt_pk_bf16_f32 v30, v24, v25
	v_cvt_pk_bf16_f32 v31, v26, v27
	global_store_dwordx4 v157, v[28:31], s[8:9]
	v_pk_mul_f32 v[158:159], v[20:21], s[56:57]
	v_pk_mul_f32 v[160:161], v[22:23], s[56:57]
	v_pk_mul_f32 v[162:163], v[16:17], s[56:57]
	v_pk_mul_f32 v[164:165], v[18:19], s[56:57]
	v_exp_f32_e32 v158, v158
	v_exp_f32_e32 v159, v159
	v_exp_f32_e32 v160, v160
	v_exp_f32_e32 v161, v161
	v_exp_f32_e32 v162, v162
	v_exp_f32_e32 v163, v163
	v_exp_f32_e32 v164, v164
	v_exp_f32_e32 v165, v165
	v_pk_add_f32 v[158:159], v[158:159], s[58:59]
	v_pk_add_f32 v[160:161], v[160:161], s[58:59]
	v_pk_add_f32 v[162:163], v[162:163], s[58:59]
	v_pk_add_f32 v[164:165], v[164:165], s[58:59]
	v_rcp_f32_e32 v158, v158
	v_rcp_f32_e32 v159, v159
	v_rcp_f32_e32 v160, v160
	v_rcp_f32_e32 v161, v161
	v_rcp_f32_e32 v162, v162
	v_rcp_f32_e32 v163, v163
	v_rcp_f32_e32 v164, v164
	v_rcp_f32_e32 v165, v165
	v_pk_mul_f32 v[20:21], v[20:21], v[158:159]
	v_pk_mul_f32 v[22:23], v[22:23], v[160:161]
	v_pk_mul_f32 v[16:17], v[16:17], v[162:163]
	v_pk_mul_f32 v[18:19], v[18:19], v[164:165]
	v_cvt_pk_bf16_f32 v20, v20, v21
	v_cvt_pk_bf16_f32 v21, v22, v23
	v_cvt_pk_bf16_f32 v22, v16, v17
	v_cvt_pk_bf16_f32 v23, v18, v19
	global_store_dwordx4 v157, v[20:23], s[8:9] offset:256
	v_add_u32_e32 v157, s20, v157
	v_pk_mul_f32 v[158:159], v[12:13], s[56:57]
	v_pk_mul_f32 v[160:161], v[14:15], s[56:57]
	v_pk_mul_f32 v[162:163], v[8:9], s[56:57]
	v_pk_mul_f32 v[164:165], v[10:11], s[56:57]
	v_exp_f32_e32 v158, v158
	v_exp_f32_e32 v159, v159
	v_exp_f32_e32 v160, v160
	v_exp_f32_e32 v161, v161
	v_exp_f32_e32 v162, v162
	v_exp_f32_e32 v163, v163
	v_exp_f32_e32 v164, v164
	v_exp_f32_e32 v165, v165
	v_pk_add_f32 v[158:159], v[158:159], s[58:59]
	v_pk_add_f32 v[160:161], v[160:161], s[58:59]
	v_pk_add_f32 v[162:163], v[162:163], s[58:59]
	v_pk_add_f32 v[164:165], v[164:165], s[58:59]
	v_rcp_f32_e32 v158, v158
	v_rcp_f32_e32 v159, v159
	v_rcp_f32_e32 v160, v160
	v_rcp_f32_e32 v161, v161
	v_rcp_f32_e32 v162, v162
	v_rcp_f32_e32 v163, v163
	v_rcp_f32_e32 v164, v164
	v_rcp_f32_e32 v165, v165
	v_pk_mul_f32 v[12:13], v[12:13], v[158:159]
	v_pk_mul_f32 v[14:15], v[14:15], v[160:161]
	v_pk_mul_f32 v[8:9], v[8:9], v[162:163]
	v_pk_mul_f32 v[10:11], v[10:11], v[164:165]
	v_cvt_pk_bf16_f32 v12, v12, v13
	v_cvt_pk_bf16_f32 v13, v14, v15
	v_cvt_pk_bf16_f32 v14, v8, v9
	v_cvt_pk_bf16_f32 v15, v10, v11
	global_store_dwordx4 v157, v[12:15], s[8:9]
	v_pk_mul_f32 v[158:159], v[4:5], s[56:57]
	v_pk_mul_f32 v[160:161], v[6:7], s[56:57]
	v_pk_mul_f32 v[162:163], v[0:1], s[56:57]
	v_pk_mul_f32 v[164:165], v[2:3], s[56:57]
	v_exp_f32_e32 v158, v158
	v_exp_f32_e32 v159, v159
	v_exp_f32_e32 v160, v160
	v_exp_f32_e32 v161, v161
	v_exp_f32_e32 v162, v162
	v_exp_f32_e32 v163, v163
	v_exp_f32_e32 v164, v164
	v_exp_f32_e32 v165, v165
	v_pk_add_f32 v[158:159], v[158:159], s[58:59]
	v_pk_add_f32 v[160:161], v[160:161], s[58:59]
	v_pk_add_f32 v[162:163], v[162:163], s[58:59]
	v_pk_add_f32 v[164:165], v[164:165], s[58:59]
	v_rcp_f32_e32 v158, v158
	v_rcp_f32_e32 v159, v159
	v_rcp_f32_e32 v160, v160
	v_rcp_f32_e32 v161, v161
	v_rcp_f32_e32 v162, v162
	v_rcp_f32_e32 v163, v163
	v_rcp_f32_e32 v164, v164
	v_rcp_f32_e32 v165, v165
	v_pk_mul_f32 v[4:5], v[4:5], v[158:159]
	v_pk_mul_f32 v[6:7], v[6:7], v[160:161]
	v_pk_mul_f32 v[0:1], v[0:1], v[162:163]
	v_pk_mul_f32 v[2:3], v[2:3], v[164:165]
	v_cvt_pk_bf16_f32 v4, v4, v5
	v_cvt_pk_bf16_f32 v5, v6, v7
	v_cvt_pk_bf16_f32 v6, v0, v1
	v_cvt_pk_bf16_f32 v7, v2, v3
	global_store_dwordx4 v157, v[4:7], s[8:9] offset:256
	s_branch .Lepi_exit
.Lepi_sig:
	v_pk_mul_f32 v[158:159], v[126:127], s[56:57]
	v_pk_mul_f32 v[160:161], v[128:129], s[56:57]
	v_pk_mul_f32 v[162:163], v[122:123], s[56:57]
	v_pk_mul_f32 v[164:165], v[124:125], s[56:57]
	v_exp_f32_e32 v158, v158
	v_exp_f32_e32 v159, v159
	v_exp_f32_e32 v160, v160
	v_exp_f32_e32 v161, v161
	v_exp_f32_e32 v162, v162
	v_exp_f32_e32 v163, v163
	v_exp_f32_e32 v164, v164
	v_exp_f32_e32 v165, v165
	v_pk_add_f32 v[158:159], v[158:159], s[58:59]
	v_pk_add_f32 v[160:161], v[160:161], s[58:59]
	v_pk_add_f32 v[162:163], v[162:163], s[58:59]
	v_pk_add_f32 v[164:165], v[164:165], s[58:59]
	v_rcp_f32_e32 v158, v158
	v_rcp_f32_e32 v159, v159
	v_rcp_f32_e32 v160, v160
	v_rcp_f32_e32 v161, v161
	v_rcp_f32_e32 v162, v162
	v_rcp_f32_e32 v163, v163
	v_rcp_f32_e32 v164, v164
	v_rcp_f32_e32 v165, v165
	v_cvt_pk_bf16_f32 v126, v158, v159
	v_cvt_pk_bf16_f32 v127, v160, v161
	v_cvt_pk_bf16_f32 v128, v162, v163
	v_cvt_pk_bf16_f32 v129, v164, v165
	global_store_dwordx4 v157, v[126:129], s[8:9]
	v_pk_mul_f32 v[158:159], v[118:119], s[56:57]
	v_pk_mul_f32 v[160:161], v[120:121], s[56:57]
	v_pk_mul_f32 v[162:163], v[114:115], s[56:57]
	v_pk_mul_f32 v[164:165], v[116:117], s[56:57]
	v_exp_f32_e32 v158, v158
	v_exp_f32_e32 v159, v159
	v_exp_f32_e32 v160, v160
	v_exp_f32_e32 v161, v161
	v_exp_f32_e32 v162, v162
	v_exp_f32_e32 v163, v163
	v_exp_f32_e32 v164, v164
	v_exp_f32_e32 v165, v165
	v_pk_add_f32 v[158:159], v[158:159], s[58:59]
	v_pk_add_f32 v[160:161], v[160:161], s[58:59]
	v_pk_add_f32 v[162:163], v[162:163], s[58:59]
	v_pk_add_f32 v[164:165], v[164:165], s[58:59]
	v_rcp_f32_e32 v158, v158
	v_rcp_f32_e32 v159, v159
	v_rcp_f32_e32 v160, v160
	v_rcp_f32_e32 v161, v161
	v_rcp_f32_e32 v162, v162
	v_rcp_f32_e32 v163, v163
	v_rcp_f32_e32 v164, v164
	v_rcp_f32_e32 v165, v165
	v_cvt_pk_bf16_f32 v118, v158, v159
	v_cvt_pk_bf16_f32 v119, v160, v161
	v_cvt_pk_bf16_f32 v120, v162, v163
	v_cvt_pk_bf16_f32 v121, v164, v165
	global_store_dwordx4 v157, v[118:121], s[8:9] offset:256
	v_add_u32_e32 v157, s20, v157
	v_pk_mul_f32 v[158:159], v[110:111], s[56:57]
	v_pk_mul_f32 v[160:161], v[112:113], s[56:57]
	v_pk_mul_f32 v[162:163], v[106:107], s[56:57]
	v_pk_mul_f32 v[164:165], v[108:109], s[56:57]
	v_exp_f32_e32 v158, v158
	v_exp_f32_e32 v159, v159
	v_exp_f32_e32 v160, v160
	v_exp_f32_e32 v161, v161
	v_exp_f32_e32 v162, v162
	v_exp_f32_e32 v163, v163
	v_exp_f32_e32 v164, v164
	v_exp_f32_e32 v165, v165
	v_pk_add_f32 v[158:159], v[158:159], s[58:59]
	v_pk_add_f32 v[160:161], v[160:161], s[58:59]
	v_pk_add_f32 v[162:163], v[162:163], s[58:59]
	v_pk_add_f32 v[164:165], v[164:165], s[58:59]
	v_rcp_f32_e32 v158, v158
	v_rcp_f32_e32 v159, v159
	v_rcp_f32_e32 v160, v160
	v_rcp_f32_e32 v161, v161
	v_rcp_f32_e32 v162, v162
	v_rcp_f32_e32 v163, v163
	v_rcp_f32_e32 v164, v164
	v_rcp_f32_e32 v165, v165
	v_cvt_pk_bf16_f32 v110, v158, v159
	v_cvt_pk_bf16_f32 v111, v160, v161
	v_cvt_pk_bf16_f32 v112, v162, v163
	v_cvt_pk_bf16_f32 v113, v164, v165
	global_store_dwordx4 v157, v[110:113], s[8:9]
	v_pk_mul_f32 v[158:159], v[102:103], s[56:57]
	v_pk_mul_f32 v[160:161], v[104:105], s[56:57]
	v_pk_mul_f32 v[162:163], v[98:99], s[56:57]
	v_pk_mul_f32 v[164:165], v[100:101], s[56:57]
	v_exp_f32_e32 v158, v158
	v_exp_f32_e32 v159, v159
	v_exp_f32_e32 v160, v160
	v_exp_f32_e32 v161, v161
	v_exp_f32_e32 v162, v162
	v_exp_f32_e32 v163, v163
	v_exp_f32_e32 v164, v164
	v_exp_f32_e32 v165, v165
	v_pk_add_f32 v[158:159], v[158:159], s[58:59]
	v_pk_add_f32 v[160:161], v[160:161], s[58:59]
	v_pk_add_f32 v[162:163], v[162:163], s[58:59]
	v_pk_add_f32 v[164:165], v[164:165], s[58:59]
	v_rcp_f32_e32 v158, v158
	v_rcp_f32_e32 v159, v159
	v_rcp_f32_e32 v160, v160
	v_rcp_f32_e32 v161, v161
	v_rcp_f32_e32 v162, v162
	v_rcp_f32_e32 v163, v163
	v_rcp_f32_e32 v164, v164
	v_rcp_f32_e32 v165, v165
	v_cvt_pk_bf16_f32 v102, v158, v159
	v_cvt_pk_bf16_f32 v103, v160, v161
	v_cvt_pk_bf16_f32 v104, v162, v163
	v_cvt_pk_bf16_f32 v105, v164, v165
	global_store_dwordx4 v157, v[102:105], s[8:9] offset:256
	v_add_u32_e32 v157, s20, v157
	v_pk_mul_f32 v[158:159], v[94:95], s[56:57]
	v_pk_mul_f32 v[160:161], v[96:97], s[56:57]
	v_pk_mul_f32 v[162:163], v[90:91], s[56:57]
	v_pk_mul_f32 v[164:165], v[92:93], s[56:57]
	v_exp_f32_e32 v158, v158
	v_exp_f32_e32 v159, v159
	v_exp_f32_e32 v160, v160
	v_exp_f32_e32 v161, v161
	v_exp_f32_e32 v162, v162
	v_exp_f32_e32 v163, v163
	v_exp_f32_e32 v164, v164
	v_exp_f32_e32 v165, v165
	v_pk_add_f32 v[158:159], v[158:159], s[58:59]
	v_pk_add_f32 v[160:161], v[160:161], s[58:59]
	v_pk_add_f32 v[162:163], v[162:163], s[58:59]
	v_pk_add_f32 v[164:165], v[164:165], s[58:59]
	v_rcp_f32_e32 v158, v158
	v_rcp_f32_e32 v159, v159
	v_rcp_f32_e32 v160, v160
	v_rcp_f32_e32 v161, v161
	v_rcp_f32_e32 v162, v162
	v_rcp_f32_e32 v163, v163
	v_rcp_f32_e32 v164, v164
	v_rcp_f32_e32 v165, v165
	v_cvt_pk_bf16_f32 v94, v158, v159
	v_cvt_pk_bf16_f32 v95, v160, v161
	v_cvt_pk_bf16_f32 v96, v162, v163
	v_cvt_pk_bf16_f32 v97, v164, v165
	global_store_dwordx4 v157, v[94:97], s[8:9]
	v_pk_mul_f32 v[158:159], v[86:87], s[56:57]
	v_pk_mul_f32 v[160:161], v[88:89], s[56:57]
	v_pk_mul_f32 v[162:163], v[82:83], s[56:57]
	v_pk_mul_f32 v[164:165], v[84:85], s[56:57]
	v_exp_f32_e32 v158, v158
	v_exp_f32_e32 v159, v159
	v_exp_f32_e32 v160, v160
	v_exp_f32_e32 v161, v161
	v_exp_f32_e32 v162, v162
	v_exp_f32_e32 v163, v163
	v_exp_f32_e32 v164, v164
	v_exp_f32_e32 v165, v165
	v_pk_add_f32 v[158:159], v[158:159], s[58:59]
	v_pk_add_f32 v[160:161], v[160:161], s[58:59]
	v_pk_add_f32 v[162:163], v[162:163], s[58:59]
	v_pk_add_f32 v[164:165], v[164:165], s[58:59]
	v_rcp_f32_e32 v158, v158
	v_rcp_f32_e32 v159, v159
	v_rcp_f32_e32 v160, v160
	v_rcp_f32_e32 v161, v161
	v_rcp_f32_e32 v162, v162
	v_rcp_f32_e32 v163, v163
	v_rcp_f32_e32 v164, v164
	v_rcp_f32_e32 v165, v165
	v_cvt_pk_bf16_f32 v86, v158, v159
	v_cvt_pk_bf16_f32 v87, v160, v161
	v_cvt_pk_bf16_f32 v88, v162, v163
	v_cvt_pk_bf16_f32 v89, v164, v165
	global_store_dwordx4 v157, v[86:89], s[8:9] offset:256
	v_add_u32_e32 v157, s20, v157
	v_pk_mul_f32 v[158:159], v[78:79], s[56:57]
	v_pk_mul_f32 v[160:161], v[80:81], s[56:57]
	v_pk_mul_f32 v[162:163], v[74:75], s[56:57]
	v_pk_mul_f32 v[164:165], v[76:77], s[56:57]
	v_exp_f32_e32 v158, v158
	v_exp_f32_e32 v159, v159
	v_exp_f32_e32 v160, v160
	v_exp_f32_e32 v161, v161
	v_exp_f32_e32 v162, v162
	v_exp_f32_e32 v163, v163
	v_exp_f32_e32 v164, v164
	v_exp_f32_e32 v165, v165
	v_pk_add_f32 v[158:159], v[158:159], s[58:59]
	v_pk_add_f32 v[160:161], v[160:161], s[58:59]
	v_pk_add_f32 v[162:163], v[162:163], s[58:59]
	v_pk_add_f32 v[164:165], v[164:165], s[58:59]
	v_rcp_f32_e32 v158, v158
	v_rcp_f32_e32 v159, v159
	v_rcp_f32_e32 v160, v160
	v_rcp_f32_e32 v161, v161
	v_rcp_f32_e32 v162, v162
	v_rcp_f32_e32 v163, v163
	v_rcp_f32_e32 v164, v164
	v_rcp_f32_e32 v165, v165
	v_cvt_pk_bf16_f32 v78, v158, v159
	v_cvt_pk_bf16_f32 v79, v160, v161
	v_cvt_pk_bf16_f32 v80, v162, v163
	v_cvt_pk_bf16_f32 v81, v164, v165
	global_store_dwordx4 v157, v[78:81], s[8:9]
	v_pk_mul_f32 v[158:159], v[70:71], s[56:57]
	v_pk_mul_f32 v[160:161], v[72:73], s[56:57]
	v_pk_mul_f32 v[162:163], v[66:67], s[56:57]
	v_pk_mul_f32 v[164:165], v[68:69], s[56:57]
	v_exp_f32_e32 v158, v158
	v_exp_f32_e32 v159, v159
	v_exp_f32_e32 v160, v160
	v_exp_f32_e32 v161, v161
	v_exp_f32_e32 v162, v162
	v_exp_f32_e32 v163, v163
	v_exp_f32_e32 v164, v164
	v_exp_f32_e32 v165, v165
	v_pk_add_f32 v[158:159], v[158:159], s[58:59]
	v_pk_add_f32 v[160:161], v[160:161], s[58:59]
	v_pk_add_f32 v[162:163], v[162:163], s[58:59]
	v_pk_add_f32 v[164:165], v[164:165], s[58:59]
	v_rcp_f32_e32 v158, v158
	v_rcp_f32_e32 v159, v159
	v_rcp_f32_e32 v160, v160
	v_rcp_f32_e32 v161, v161
	v_rcp_f32_e32 v162, v162
	v_rcp_f32_e32 v163, v163
	v_rcp_f32_e32 v164, v164
	v_rcp_f32_e32 v165, v165
	v_cvt_pk_bf16_f32 v70, v158, v159
	v_cvt_pk_bf16_f32 v71, v160, v161
	v_cvt_pk_bf16_f32 v72, v162, v163
	v_cvt_pk_bf16_f32 v73, v164, v165
	global_store_dwordx4 v157, v[70:73], s[8:9] offset:256
	v_add_u32_e32 v157, s36, v157
	v_pk_mul_f32 v[158:159], v[60:61], s[56:57]
	v_pk_mul_f32 v[160:161], v[62:63], s[56:57]
	v_pk_mul_f32 v[162:163], v[56:57], s[56:57]
	v_pk_mul_f32 v[164:165], v[58:59], s[56:57]
	v_exp_f32_e32 v158, v158
	v_exp_f32_e32 v159, v159
	v_exp_f32_e32 v160, v160
	v_exp_f32_e32 v161, v161
	v_exp_f32_e32 v162, v162
	v_exp_f32_e32 v163, v163
	v_exp_f32_e32 v164, v164
	v_exp_f32_e32 v165, v165
	v_pk_add_f32 v[158:159], v[158:159], s[58:59]
	v_pk_add_f32 v[160:161], v[160:161], s[58:59]
	v_pk_add_f32 v[162:163], v[162:163], s[58:59]
	v_pk_add_f32 v[164:165], v[164:165], s[58:59]
	v_rcp_f32_e32 v158, v158
	v_rcp_f32_e32 v159, v159
	v_rcp_f32_e32 v160, v160
	v_rcp_f32_e32 v161, v161
	v_rcp_f32_e32 v162, v162
	v_rcp_f32_e32 v163, v163
	v_rcp_f32_e32 v164, v164
	v_rcp_f32_e32 v165, v165
	v_cvt_pk_bf16_f32 v60, v158, v159
	v_cvt_pk_bf16_f32 v61, v160, v161
	v_cvt_pk_bf16_f32 v62, v162, v163
	v_cvt_pk_bf16_f32 v63, v164, v165
	global_store_dwordx4 v157, v[60:63], s[8:9]
	v_pk_mul_f32 v[158:159], v[52:53], s[56:57]
	v_pk_mul_f32 v[160:161], v[54:55], s[56:57]
	v_pk_mul_f32 v[162:163], v[48:49], s[56:57]
	v_pk_mul_f32 v[164:165], v[50:51], s[56:57]
	v_exp_f32_e32 v158, v158
	v_exp_f32_e32 v159, v159
	v_exp_f32_e32 v160, v160
	v_exp_f32_e32 v161, v161
	v_exp_f32_e32 v162, v162
	v_exp_f32_e32 v163, v163
	v_exp_f32_e32 v164, v164
	v_exp_f32_e32 v165, v165
	v_pk_add_f32 v[158:159], v[158:159], s[58:59]
	v_pk_add_f32 v[160:161], v[160:161], s[58:59]
	v_pk_add_f32 v[162:163], v[162:163], s[58:59]
	v_pk_add_f32 v[164:165], v[164:165], s[58:59]
	v_rcp_f32_e32 v158, v158
	v_rcp_f32_e32 v159, v159
	v_rcp_f32_e32 v160, v160
	v_rcp_f32_e32 v161, v161
	v_rcp_f32_e32 v162, v162
	v_rcp_f32_e32 v163, v163
	v_rcp_f32_e32 v164, v164
	v_rcp_f32_e32 v165, v165
	v_cvt_pk_bf16_f32 v52, v158, v159
	v_cvt_pk_bf16_f32 v53, v160, v161
	v_cvt_pk_bf16_f32 v54, v162, v163
	v_cvt_pk_bf16_f32 v55, v164, v165
	global_store_dwordx4 v157, v[52:55], s[8:9] offset:256
	v_add_u32_e32 v157, s20, v157
	v_pk_mul_f32 v[158:159], v[44:45], s[56:57]
	v_pk_mul_f32 v[160:161], v[46:47], s[56:57]
	v_pk_mul_f32 v[162:163], v[40:41], s[56:57]
	v_pk_mul_f32 v[164:165], v[42:43], s[56:57]
	v_exp_f32_e32 v158, v158
	v_exp_f32_e32 v159, v159
	v_exp_f32_e32 v160, v160
	v_exp_f32_e32 v161, v161
	v_exp_f32_e32 v162, v162
	v_exp_f32_e32 v163, v163
	v_exp_f32_e32 v164, v164
	v_exp_f32_e32 v165, v165
	v_pk_add_f32 v[158:159], v[158:159], s[58:59]
	v_pk_add_f32 v[160:161], v[160:161], s[58:59]
	v_pk_add_f32 v[162:163], v[162:163], s[58:59]
	v_pk_add_f32 v[164:165], v[164:165], s[58:59]
	v_rcp_f32_e32 v158, v158
	v_rcp_f32_e32 v159, v159
	v_rcp_f32_e32 v160, v160
	v_rcp_f32_e32 v161, v161
	v_rcp_f32_e32 v162, v162
	v_rcp_f32_e32 v163, v163
	v_rcp_f32_e32 v164, v164
	v_rcp_f32_e32 v165, v165
	v_cvt_pk_bf16_f32 v44, v158, v159
	v_cvt_pk_bf16_f32 v45, v160, v161
	v_cvt_pk_bf16_f32 v46, v162, v163
	v_cvt_pk_bf16_f32 v47, v164, v165
	global_store_dwordx4 v157, v[44:47], s[8:9]
	v_pk_mul_f32 v[158:159], v[36:37], s[56:57]
	v_pk_mul_f32 v[160:161], v[38:39], s[56:57]
	v_pk_mul_f32 v[162:163], v[32:33], s[56:57]
	v_pk_mul_f32 v[164:165], v[34:35], s[56:57]
	v_exp_f32_e32 v158, v158
	v_exp_f32_e32 v159, v159
	v_exp_f32_e32 v160, v160
	v_exp_f32_e32 v161, v161
	v_exp_f32_e32 v162, v162
	v_exp_f32_e32 v163, v163
	v_exp_f32_e32 v164, v164
	v_exp_f32_e32 v165, v165
	v_pk_add_f32 v[158:159], v[158:159], s[58:59]
	v_pk_add_f32 v[160:161], v[160:161], s[58:59]
	v_pk_add_f32 v[162:163], v[162:163], s[58:59]
	v_pk_add_f32 v[164:165], v[164:165], s[58:59]
	v_rcp_f32_e32 v158, v158
	v_rcp_f32_e32 v159, v159
	v_rcp_f32_e32 v160, v160
	v_rcp_f32_e32 v161, v161
	v_rcp_f32_e32 v162, v162
	v_rcp_f32_e32 v163, v163
	v_rcp_f32_e32 v164, v164
	v_rcp_f32_e32 v165, v165
	v_cvt_pk_bf16_f32 v36, v158, v159
	v_cvt_pk_bf16_f32 v37, v160, v161
	v_cvt_pk_bf16_f32 v38, v162, v163
	v_cvt_pk_bf16_f32 v39, v164, v165
	global_store_dwordx4 v157, v[36:39], s[8:9] offset:256
	v_add_u32_e32 v157, s20, v157
	v_pk_mul_f32 v[158:159], v[28:29], s[56:57]
	v_pk_mul_f32 v[160:161], v[30:31], s[56:57]
	v_pk_mul_f32 v[162:163], v[24:25], s[56:57]
	v_pk_mul_f32 v[164:165], v[26:27], s[56:57]
	v_exp_f32_e32 v158, v158
	v_exp_f32_e32 v159, v159
	v_exp_f32_e32 v160, v160
	v_exp_f32_e32 v161, v161
	v_exp_f32_e32 v162, v162
	v_exp_f32_e32 v163, v163
	v_exp_f32_e32 v164, v164
	v_exp_f32_e32 v165, v165
	v_pk_add_f32 v[158:159], v[158:159], s[58:59]
	v_pk_add_f32 v[160:161], v[160:161], s[58:59]
	v_pk_add_f32 v[162:163], v[162:163], s[58:59]
	v_pk_add_f32 v[164:165], v[164:165], s[58:59]
	v_rcp_f32_e32 v158, v158
	v_rcp_f32_e32 v159, v159
	v_rcp_f32_e32 v160, v160
	v_rcp_f32_e32 v161, v161
	v_rcp_f32_e32 v162, v162
	v_rcp_f32_e32 v163, v163
	v_rcp_f32_e32 v164, v164
	v_rcp_f32_e32 v165, v165
	v_cvt_pk_bf16_f32 v28, v158, v159
	v_cvt_pk_bf16_f32 v29, v160, v161
	v_cvt_pk_bf16_f32 v30, v162, v163
	v_cvt_pk_bf16_f32 v31, v164, v165
	global_store_dwordx4 v157, v[28:31], s[8:9]
	v_pk_mul_f32 v[158:159], v[20:21], s[56:57]
	v_pk_mul_f32 v[160:161], v[22:23], s[56:57]
	v_pk_mul_f32 v[162:163], v[16:17], s[56:57]
	v_pk_mul_f32 v[164:165], v[18:19], s[56:57]
	v_exp_f32_e32 v158, v158
	v_exp_f32_e32 v159, v159
	v_exp_f32_e32 v160, v160
	v_exp_f32_e32 v161, v161
	v_exp_f32_e32 v162, v162
	v_exp_f32_e32 v163, v163
	v_exp_f32_e32 v164, v164
	v_exp_f32_e32 v165, v165
	v_pk_add_f32 v[158:159], v[158:159], s[58:59]
	v_pk_add_f32 v[160:161], v[160:161], s[58:59]
	v_pk_add_f32 v[162:163], v[162:163], s[58:59]
	v_pk_add_f32 v[164:165], v[164:165], s[58:59]
	v_rcp_f32_e32 v158, v158
	v_rcp_f32_e32 v159, v159
	v_rcp_f32_e32 v160, v160
	v_rcp_f32_e32 v161, v161
	v_rcp_f32_e32 v162, v162
	v_rcp_f32_e32 v163, v163
	v_rcp_f32_e32 v164, v164
	v_rcp_f32_e32 v165, v165
	v_cvt_pk_bf16_f32 v20, v158, v159
	v_cvt_pk_bf16_f32 v21, v160, v161
	v_cvt_pk_bf16_f32 v22, v162, v163
	v_cvt_pk_bf16_f32 v23, v164, v165
	global_store_dwordx4 v157, v[20:23], s[8:9] offset:256
	v_add_u32_e32 v157, s20, v157
	v_pk_mul_f32 v[158:159], v[12:13], s[56:57]
	v_pk_mul_f32 v[160:161], v[14:15], s[56:57]
	v_pk_mul_f32 v[162:163], v[8:9], s[56:57]
	v_pk_mul_f32 v[164:165], v[10:11], s[56:57]
	v_exp_f32_e32 v158, v158
	v_exp_f32_e32 v159, v159
	v_exp_f32_e32 v160, v160
	v_exp_f32_e32 v161, v161
	v_exp_f32_e32 v162, v162
	v_exp_f32_e32 v163, v163
	v_exp_f32_e32 v164, v164
	v_exp_f32_e32 v165, v165
	v_pk_add_f32 v[158:159], v[158:159], s[58:59]
	v_pk_add_f32 v[160:161], v[160:161], s[58:59]
	v_pk_add_f32 v[162:163], v[162:163], s[58:59]
	v_pk_add_f32 v[164:165], v[164:165], s[58:59]
	v_rcp_f32_e32 v158, v158
	v_rcp_f32_e32 v159, v159
	v_rcp_f32_e32 v160, v160
	v_rcp_f32_e32 v161, v161
	v_rcp_f32_e32 v162, v162
	v_rcp_f32_e32 v163, v163
	v_rcp_f32_e32 v164, v164
	v_rcp_f32_e32 v165, v165
	v_cvt_pk_bf16_f32 v12, v158, v159
	v_cvt_pk_bf16_f32 v13, v160, v161
	v_cvt_pk_bf16_f32 v14, v162, v163
	v_cvt_pk_bf16_f32 v15, v164, v165
	global_store_dwordx4 v157, v[12:15], s[8:9]
	v_pk_mul_f32 v[158:159], v[4:5], s[56:57]
	v_pk_mul_f32 v[160:161], v[6:7], s[56:57]
	v_pk_mul_f32 v[162:163], v[0:1], s[56:57]
	v_pk_mul_f32 v[164:165], v[2:3], s[56:57]
	v_exp_f32_e32 v158, v158
	v_exp_f32_e32 v159, v159
	v_exp_f32_e32 v160, v160
	v_exp_f32_e32 v161, v161
	v_exp_f32_e32 v162, v162
	v_exp_f32_e32 v163, v163
	v_exp_f32_e32 v164, v164
	v_exp_f32_e32 v165, v165
	v_pk_add_f32 v[158:159], v[158:159], s[58:59]
	v_pk_add_f32 v[160:161], v[160:161], s[58:59]
	v_pk_add_f32 v[162:163], v[162:163], s[58:59]
	v_pk_add_f32 v[164:165], v[164:165], s[58:59]
	v_rcp_f32_e32 v158, v158
	v_rcp_f32_e32 v159, v159
	v_rcp_f32_e32 v160, v160
	v_rcp_f32_e32 v161, v161
	v_rcp_f32_e32 v162, v162
	v_rcp_f32_e32 v163, v163
	v_rcp_f32_e32 v164, v164
	v_rcp_f32_e32 v165, v165
	v_cvt_pk_bf16_f32 v4, v158, v159
	v_cvt_pk_bf16_f32 v5, v160, v161
	v_cvt_pk_bf16_f32 v6, v162, v163
	v_cvt_pk_bf16_f32 v7, v164, v165
	global_store_dwordx4 v157, v[4:7], s[8:9] offset:256
	s_branch .Lepi_exit
.Lepi_log:
	s_lshl_b32 s4, s2, 10
	s_sub_u32 s4, s4, 0x1000
	s_add_u32 s54, s90, 0x3400000
	s_addc_u32 s55, s91, 0
	s_add_u32 s54, s54, s4
	s_addc_u32 s55, s55, 0
	s_lshl_b32 s4, s0, 7
	v_lshl_add_u32 v166, v132, 5, s4
	global_load_dwordx4 v[196:199], v166, s[54:55]
	global_load_dwordx4 v[134:137], v166, s[54:55] offset:16
	s_mov_b32 s2, 0x3f317217
	s_mov_b32 s3, 0x3f317217
	s_mov_b32 s18, 0x3377d1cf
	s_mov_b32 s19, 0x3377d1cf
	s_waitcnt vmcnt(0)
	v_pk_mul_f32 v[158:159], v[126:127], s[56:57]
	v_pk_mul_f32 v[160:161], v[128:129], s[56:57]
	v_pk_mul_f32 v[162:163], v[122:123], s[56:57]
	v_pk_mul_f32 v[164:165], v[124:125], s[56:57]
	v_exp_f32_e32 v158, v158
	v_exp_f32_e32 v159, v159
	v_exp_f32_e32 v160, v160
	v_exp_f32_e32 v161, v161
	v_exp_f32_e32 v162, v162
	v_exp_f32_e32 v163, v163
	v_exp_f32_e32 v164, v164
	v_exp_f32_e32 v165, v165
	v_pk_add_f32 v[158:159], v[158:159], s[58:59]
	v_pk_add_f32 v[160:161], v[160:161], s[58:59]
	v_pk_add_f32 v[162:163], v[162:163], s[58:59]
	v_pk_add_f32 v[164:165], v[164:165], s[58:59]
	v_rcp_f32_e32 v158, v158
	v_rcp_f32_e32 v159, v159
	v_rcp_f32_e32 v160, v160
	v_rcp_f32_e32 v161, v161
	v_rcp_f32_e32 v162, v162
	v_rcp_f32_e32 v163, v163
	v_rcp_f32_e32 v164, v164
	v_rcp_f32_e32 v165, v165
	v_pk_add_f32 v[130:131], s[58:59], v[196:197] neg_lo:[0,1] neg_hi:[0,1]
	v_pk_fma_f32 v[158:159], v[158:159], v[130:131], v[196:197]
	v_pk_add_f32 v[132:133], s[58:59], v[198:199] neg_lo:[0,1] neg_hi:[0,1]
	v_pk_fma_f32 v[160:161], v[160:161], v[132:133], v[198:199]
	v_pk_add_f32 v[130:131], s[58:59], v[134:135] neg_lo:[0,1] neg_hi:[0,1]
	v_pk_fma_f32 v[162:163], v[162:163], v[130:131], v[134:135]
	v_pk_add_f32 v[132:133], s[58:59], v[136:137] neg_lo:[0,1] neg_hi:[0,1]
	v_pk_fma_f32 v[164:165], v[164:165], v[132:133], v[136:137]
	v_log_f32_e32 v158, v158
	v_log_f32_e32 v159, v159
	v_log_f32_e32 v160, v160
	v_log_f32_e32 v161, v161
	v_log_f32_e32 v162, v162
	v_log_f32_e32 v163, v163
	v_log_f32_e32 v164, v164
	v_log_f32_e32 v165, v165
	v_pk_mul_f32 v[126:127], v[158:159], s[2:3]
	v_pk_mul_f32 v[128:129], v[160:161], s[2:3]
	v_pk_mul_f32 v[122:123], v[162:163], s[2:3]
	v_pk_mul_f32 v[124:125], v[164:165], s[2:3]
	v_pk_fma_f32 v[126:127], v[158:159], s[2:3], v[126:127] neg_lo:[0,0,1] neg_hi:[0,0,1]
	v_pk_fma_f32 v[128:129], v[160:161], s[2:3], v[128:129] neg_lo:[0,0,1] neg_hi:[0,0,1]
	v_pk_fma_f32 v[122:123], v[162:163], s[2:3], v[122:123] neg_lo:[0,0,1] neg_hi:[0,0,1]
	v_pk_fma_f32 v[124:125], v[164:165], s[2:3], v[124:125] neg_lo:[0,0,1] neg_hi:[0,0,1]
	v_pk_fma_f32 v[126:127], v[158:159], s[18:19], v[126:127]
	v_pk_fma_f32 v[128:129], v[160:161], s[18:19], v[128:129]
	v_pk_fma_f32 v[122:123], v[162:163], s[18:19], v[122:123]
	v_pk_fma_f32 v[124:125], v[164:165], s[18:19], v[124:125]
	v_pk_fma_f32 v[126:127], v[158:159], s[2:3], v[126:127]
	v_pk_fma_f32 v[128:129], v[160:161], s[2:3], v[128:129]
	v_pk_fma_f32 v[122:123], v[162:163], s[2:3], v[122:123]
	v_pk_fma_f32 v[124:125], v[164:165], s[2:3], v[124:125]
	v_cvt_pk_bf16_f32 v126, v126, v127
	v_cvt_pk_bf16_f32 v127, v128, v129
	v_cvt_pk_bf16_f32 v128, v122, v123
	v_cvt_pk_bf16_f32 v129, v124, v125
	global_store_dwordx4 v157, v[126:129], s[8:9]
	s_nop 1
	global_load_dwordx4 v[122:125], v166, s[54:55] offset:512
	global_load_dwordx4 v[126:129], v166, s[54:55] offset:528
	v_add_u32_e32 v157, s20, v157
	v_pk_mul_f32 v[158:159], v[110:111], s[56:57]
	v_pk_mul_f32 v[160:161], v[112:113], s[56:57]
	v_pk_mul_f32 v[162:163], v[106:107], s[56:57]
	v_pk_mul_f32 v[164:165], v[108:109], s[56:57]
	v_exp_f32_e32 v158, v158
	v_exp_f32_e32 v159, v159
	v_exp_f32_e32 v160, v160
	v_exp_f32_e32 v161, v161
	v_exp_f32_e32 v162, v162
	v_exp_f32_e32 v163, v163
	v_exp_f32_e32 v164, v164
	v_exp_f32_e32 v165, v165
	v_pk_add_f32 v[158:159], v[158:159], s[58:59]
	v_pk_add_f32 v[160:161], v[160:161], s[58:59]
	v_pk_add_f32 v[162:163], v[162:163], s[58:59]
	v_pk_add_f32 v[164:165], v[164:165], s[58:59]
	v_rcp_f32_e32 v158, v158
	v_rcp_f32_e32 v159, v159
	v_rcp_f32_e32 v160, v160
	v_rcp_f32_e32 v161, v161
	v_rcp_f32_e32 v162, v162
	v_rcp_f32_e32 v163, v163
	v_rcp_f32_e32 v164, v164
	v_rcp_f32_e32 v165, v165
	v_pk_add_f32 v[130:131], s[58:59], v[196:197] neg_lo:[0,1] neg_hi:[0,1]
	v_pk_fma_f32 v[158:159], v[158:159], v[130:131], v[196:197]
	v_pk_add_f32 v[132:133], s[58:59], v[198:199] neg_lo:[0,1] neg_hi:[0,1]
	v_pk_fma_f32 v[160:161], v[160:161], v[132:133], v[198:199]
	v_pk_add_f32 v[130:131], s[58:59], v[134:135] neg_lo:[0,1] neg_hi:[0,1]
	v_pk_fma_f32 v[162:163], v[162:163], v[130:131], v[134:135]
	v_pk_add_f32 v[132:133], s[58:59], v[136:137] neg_lo:[0,1] neg_hi:[0,1]
	v_pk_fma_f32 v[164:165], v[164:165], v[132:133], v[136:137]
	v_log_f32_e32 v158, v158
	v_log_f32_e32 v159, v159
	v_log_f32_e32 v160, v160
	v_log_f32_e32 v161, v161
	v_log_f32_e32 v162, v162
	v_log_f32_e32 v163, v163
	v_log_f32_e32 v164, v164
	v_log_f32_e32 v165, v165
	v_pk_mul_f32 v[110:111], v[158:159], s[2:3]
	v_pk_mul_f32 v[112:113], v[160:161], s[2:3]
	v_pk_mul_f32 v[106:107], v[162:163], s[2:3]
	v_pk_mul_f32 v[108:109], v[164:165], s[2:3]
	v_pk_fma_f32 v[110:111], v[158:159], s[2:3], v[110:111] neg_lo:[0,0,1] neg_hi:[0,0,1]
	v_pk_fma_f32 v[112:113], v[160:161], s[2:3], v[112:113] neg_lo:[0,0,1] neg_hi:[0,0,1]
	v_pk_fma_f32 v[106:107], v[162:163], s[2:3], v[106:107] neg_lo:[0,0,1] neg_hi:[0,0,1]
	v_pk_fma_f32 v[108:109], v[164:165], s[2:3], v[108:109] neg_lo:[0,0,1] neg_hi:[0,0,1]
	v_pk_fma_f32 v[110:111], v[158:159], s[18:19], v[110:111]
	v_pk_fma_f32 v[112:113], v[160:161], s[18:19], v[112:113]
	v_pk_fma_f32 v[106:107], v[162:163], s[18:19], v[106:107]
	v_pk_fma_f32 v[108:109], v[164:165], s[18:19], v[108:109]
	v_pk_fma_f32 v[110:111], v[158:159], s[2:3], v[110:111]
	v_pk_fma_f32 v[112:113], v[160:161], s[2:3], v[112:113]
	v_pk_fma_f32 v[106:107], v[162:163], s[2:3], v[106:107]
	v_pk_fma_f32 v[108:109], v[164:165], s[2:3], v[108:109]
	v_cvt_pk_bf16_f32 v110, v110, v111
	v_cvt_pk_bf16_f32 v111, v112, v113
	v_cvt_pk_bf16_f32 v112, v106, v107
	v_cvt_pk_bf16_f32 v113, v108, v109
	global_store_dwordx4 v157, v[110:113], s[8:9]
	v_add_u32_e32 v157, s20, v157
	v_pk_mul_f32 v[158:159], v[94:95], s[56:57]
	v_pk_mul_f32 v[160:161], v[96:97], s[56:57]
	v_pk_mul_f32 v[162:163], v[90:91], s[56:57]
	v_pk_mul_f32 v[164:165], v[92:93], s[56:57]
	v_exp_f32_e32 v158, v158
	v_exp_f32_e32 v159, v159
	v_exp_f32_e32 v160, v160
	v_exp_f32_e32 v161, v161
	v_exp_f32_e32 v162, v162
	v_exp_f32_e32 v163, v163
	v_exp_f32_e32 v164, v164
	v_exp_f32_e32 v165, v165
	v_pk_add_f32 v[158:159], v[158:159], s[58:59]
	v_pk_add_f32 v[160:161], v[160:161], s[58:59]
	v_pk_add_f32 v[162:163], v[162:163], s[58:59]
	v_pk_add_f32 v[164:165], v[164:165], s[58:59]
	v_rcp_f32_e32 v158, v158
	v_rcp_f32_e32 v159, v159
	v_rcp_f32_e32 v160, v160
	v_rcp_f32_e32 v161, v161
	v_rcp_f32_e32 v162, v162
	v_rcp_f32_e32 v163, v163
	v_rcp_f32_e32 v164, v164
	v_rcp_f32_e32 v165, v165
	v_pk_add_f32 v[130:131], s[58:59], v[196:197] neg_lo:[0,1] neg_hi:[0,1]
	v_pk_fma_f32 v[158:159], v[158:159], v[130:131], v[196:197]
	v_pk_add_f32 v[132:133], s[58:59], v[198:199] neg_lo:[0,1] neg_hi:[0,1]
	v_pk_fma_f32 v[160:161], v[160:161], v[132:133], v[198:199]
	v_pk_add_f32 v[130:131], s[58:59], v[134:135] neg_lo:[0,1] neg_hi:[0,1]
	v_pk_fma_f32 v[162:163], v[162:163], v[130:131], v[134:135]
	v_pk_add_f32 v[132:133], s[58:59], v[136:137] neg_lo:[0,1] neg_hi:[0,1]
	v_pk_fma_f32 v[164:165], v[164:165], v[132:133], v[136:137]
	v_log_f32_e32 v158, v158
	v_log_f32_e32 v159, v159
	v_log_f32_e32 v160, v160
	v_log_f32_e32 v161, v161
	v_log_f32_e32 v162, v162
	v_log_f32_e32 v163, v163
	v_log_f32_e32 v164, v164
	v_log_f32_e32 v165, v165
	v_pk_mul_f32 v[94:95], v[158:159], s[2:3]
	v_pk_mul_f32 v[96:97], v[160:161], s[2:3]
	v_pk_mul_f32 v[90:91], v[162:163], s[2:3]
	v_pk_mul_f32 v[92:93], v[164:165], s[2:3]
	v_pk_fma_f32 v[94:95], v[158:159], s[2:3], v[94:95] neg_lo:[0,0,1] neg_hi:[0,0,1]
	v_pk_fma_f32 v[96:97], v[160:161], s[2:3], v[96:97] neg_lo:[0,0,1] neg_hi:[0,0,1]
	v_pk_fma_f32 v[90:91], v[162:163], s[2:3], v[90:91] neg_lo:[0,0,1] neg_hi:[0,0,1]
	v_pk_fma_f32 v[92:93], v[164:165], s[2:3], v[92:93] neg_lo:[0,0,1] neg_hi:[0,0,1]
	v_pk_fma_f32 v[94:95], v[158:159], s[18:19], v[94:95]
	v_pk_fma_f32 v[96:97], v[160:161], s[18:19], v[96:97]
	v_pk_fma_f32 v[90:91], v[162:163], s[18:19], v[90:91]
	v_pk_fma_f32 v[92:93], v[164:165], s[18:19], v[92:93]
	v_pk_fma_f32 v[94:95], v[158:159], s[2:3], v[94:95]
	v_pk_fma_f32 v[96:97], v[160:161], s[2:3], v[96:97]
	v_pk_fma_f32 v[90:91], v[162:163], s[2:3], v[90:91]
	v_pk_fma_f32 v[92:93], v[164:165], s[2:3], v[92:93]
	v_cvt_pk_bf16_f32 v94, v94, v95
	v_cvt_pk_bf16_f32 v95, v96, v97
	v_cvt_pk_bf16_f32 v96, v90, v91
	v_cvt_pk_bf16_f32 v97, v92, v93
	global_store_dwordx4 v157, v[94:97], s[8:9]
	v_add_u32_e32 v157, s20, v157
	v_pk_mul_f32 v[158:159], v[78:79], s[56:57]
	v_pk_mul_f32 v[160:161], v[80:81], s[56:57]
	v_pk_mul_f32 v[162:163], v[74:75], s[56:57]
	v_pk_mul_f32 v[164:165], v[76:77], s[56:57]
	v_exp_f32_e32 v158, v158
	v_exp_f32_e32 v159, v159
	v_exp_f32_e32 v160, v160
	v_exp_f32_e32 v161, v161
	v_exp_f32_e32 v162, v162
	v_exp_f32_e32 v163, v163
	v_exp_f32_e32 v164, v164
	v_exp_f32_e32 v165, v165
	v_pk_add_f32 v[158:159], v[158:159], s[58:59]
	v_pk_add_f32 v[160:161], v[160:161], s[58:59]
	v_pk_add_f32 v[162:163], v[162:163], s[58:59]
	v_pk_add_f32 v[164:165], v[164:165], s[58:59]
	v_rcp_f32_e32 v158, v158
	v_rcp_f32_e32 v159, v159
	v_rcp_f32_e32 v160, v160
	v_rcp_f32_e32 v161, v161
	v_rcp_f32_e32 v162, v162
	v_rcp_f32_e32 v163, v163
	v_rcp_f32_e32 v164, v164
	v_rcp_f32_e32 v165, v165
	v_pk_add_f32 v[130:131], s[58:59], v[196:197] neg_lo:[0,1] neg_hi:[0,1]
	v_pk_fma_f32 v[158:159], v[158:159], v[130:131], v[196:197]
	v_pk_add_f32 v[132:133], s[58:59], v[198:199] neg_lo:[0,1] neg_hi:[0,1]
	v_pk_fma_f32 v[160:161], v[160:161], v[132:133], v[198:199]
	v_pk_add_f32 v[130:131], s[58:59], v[134:135] neg_lo:[0,1] neg_hi:[0,1]
	v_pk_fma_f32 v[162:163], v[162:163], v[130:131], v[134:135]
	v_pk_add_f32 v[132:133], s[58:59], v[136:137] neg_lo:[0,1] neg_hi:[0,1]
	v_pk_fma_f32 v[164:165], v[164:165], v[132:133], v[136:137]
	v_log_f32_e32 v158, v158
	v_log_f32_e32 v159, v159
	v_log_f32_e32 v160, v160
	v_log_f32_e32 v161, v161
	v_log_f32_e32 v162, v162
	v_log_f32_e32 v163, v163
	v_log_f32_e32 v164, v164
	v_log_f32_e32 v165, v165
	v_pk_mul_f32 v[78:79], v[158:159], s[2:3]
	v_pk_mul_f32 v[80:81], v[160:161], s[2:3]
	v_pk_mul_f32 v[74:75], v[162:163], s[2:3]
	v_pk_mul_f32 v[76:77], v[164:165], s[2:3]
	v_pk_fma_f32 v[78:79], v[158:159], s[2:3], v[78:79] neg_lo:[0,0,1] neg_hi:[0,0,1]
	v_pk_fma_f32 v[80:81], v[160:161], s[2:3], v[80:81] neg_lo:[0,0,1] neg_hi:[0,0,1]
	v_pk_fma_f32 v[74:75], v[162:163], s[2:3], v[74:75] neg_lo:[0,0,1] neg_hi:[0,0,1]
	v_pk_fma_f32 v[76:77], v[164:165], s[2:3], v[76:77] neg_lo:[0,0,1] neg_hi:[0,0,1]
	v_pk_fma_f32 v[78:79], v[158:159], s[18:19], v[78:79]
	v_pk_fma_f32 v[80:81], v[160:161], s[18:19], v[80:81]
	v_pk_fma_f32 v[74:75], v[162:163], s[18:19], v[74:75]
	v_pk_fma_f32 v[76:77], v[164:165], s[18:19], v[76:77]
	v_pk_fma_f32 v[78:79], v[158:159], s[2:3], v[78:79]
	v_pk_fma_f32 v[80:81], v[160:161], s[2:3], v[80:81]
	v_pk_fma_f32 v[74:75], v[162:163], s[2:3], v[74:75]
	v_pk_fma_f32 v[76:77], v[164:165], s[2:3], v[76:77]
	v_cvt_pk_bf16_f32 v78, v78, v79
	v_cvt_pk_bf16_f32 v79, v80, v81
	v_cvt_pk_bf16_f32 v80, v74, v75
	v_cvt_pk_bf16_f32 v81, v76, v77
	global_store_dwordx4 v157, v[78:81], s[8:9]
	v_add_u32_e32 v157, s36, v157
	v_pk_mul_f32 v[158:159], v[60:61], s[56:57]
	v_pk_mul_f32 v[160:161], v[62:63], s[56:57]
	v_pk_mul_f32 v[162:163], v[56:57], s[56:57]
	v_pk_mul_f32 v[164:165], v[58:59], s[56:57]
	v_exp_f32_e32 v158, v158
	v_exp_f32_e32 v159, v159
	v_exp_f32_e32 v160, v160
	v_exp_f32_e32 v161, v161
	v_exp_f32_e32 v162, v162
	v_exp_f32_e32 v163, v163
	v_exp_f32_e32 v164, v164
	v_exp_f32_e32 v165, v165
	v_pk_add_f32 v[158:159], v[158:159], s[58:59]
	v_pk_add_f32 v[160:161], v[160:161], s[58:59]
	v_pk_add_f32 v[162:163], v[162:163], s[58:59]
	v_pk_add_f32 v[164:165], v[164:165], s[58:59]
	v_rcp_f32_e32 v158, v158
	v_rcp_f32_e32 v159, v159
	v_rcp_f32_e32 v160, v160
	v_rcp_f32_e32 v161, v161
	v_rcp_f32_e32 v162, v162
	v_rcp_f32_e32 v163, v163
	v_rcp_f32_e32 v164, v164
	v_rcp_f32_e32 v165, v165
	v_pk_add_f32 v[130:131], s[58:59], v[196:197] neg_lo:[0,1] neg_hi:[0,1]
	v_pk_fma_f32 v[158:159], v[158:159], v[130:131], v[196:197]
	v_pk_add_f32 v[132:133], s[58:59], v[198:199] neg_lo:[0,1] neg_hi:[0,1]
	v_pk_fma_f32 v[160:161], v[160:161], v[132:133], v[198:199]
	v_pk_add_f32 v[130:131], s[58:59], v[134:135] neg_lo:[0,1] neg_hi:[0,1]
	v_pk_fma_f32 v[162:163], v[162:163], v[130:131], v[134:135]
	v_pk_add_f32 v[132:133], s[58:59], v[136:137] neg_lo:[0,1] neg_hi:[0,1]
	v_pk_fma_f32 v[164:165], v[164:165], v[132:133], v[136:137]
	v_log_f32_e32 v158, v158
	v_log_f32_e32 v159, v159
	v_log_f32_e32 v160, v160
	v_log_f32_e32 v161, v161
	v_log_f32_e32 v162, v162
	v_log_f32_e32 v163, v163
	v_log_f32_e32 v164, v164
	v_log_f32_e32 v165, v165
	v_pk_mul_f32 v[60:61], v[158:159], s[2:3]
	v_pk_mul_f32 v[62:63], v[160:161], s[2:3]
	v_pk_mul_f32 v[56:57], v[162:163], s[2:3]
	v_pk_mul_f32 v[58:59], v[164:165], s[2:3]
	v_pk_fma_f32 v[60:61], v[158:159], s[2:3], v[60:61] neg_lo:[0,0,1] neg_hi:[0,0,1]
	v_pk_fma_f32 v[62:63], v[160:161], s[2:3], v[62:63] neg_lo:[0,0,1] neg_hi:[0,0,1]
	v_pk_fma_f32 v[56:57], v[162:163], s[2:3], v[56:57] neg_lo:[0,0,1] neg_hi:[0,0,1]
	v_pk_fma_f32 v[58:59], v[164:165], s[2:3], v[58:59] neg_lo:[0,0,1] neg_hi:[0,0,1]
	v_pk_fma_f32 v[60:61], v[158:159], s[18:19], v[60:61]
	v_pk_fma_f32 v[62:63], v[160:161], s[18:19], v[62:63]
	v_pk_fma_f32 v[56:57], v[162:163], s[18:19], v[56:57]
	v_pk_fma_f32 v[58:59], v[164:165], s[18:19], v[58:59]
	v_pk_fma_f32 v[60:61], v[158:159], s[2:3], v[60:61]
	v_pk_fma_f32 v[62:63], v[160:161], s[2:3], v[62:63]
	v_pk_fma_f32 v[56:57], v[162:163], s[2:3], v[56:57]
	v_pk_fma_f32 v[58:59], v[164:165], s[2:3], v[58:59]
	v_cvt_pk_bf16_f32 v60, v60, v61
	v_cvt_pk_bf16_f32 v61, v62, v63
	v_cvt_pk_bf16_f32 v62, v56, v57
	v_cvt_pk_bf16_f32 v63, v58, v59
	global_store_dwordx4 v157, v[60:63], s[8:9]
	v_add_u32_e32 v157, s20, v157
	v_pk_mul_f32 v[158:159], v[44:45], s[56:57]
	v_pk_mul_f32 v[160:161], v[46:47], s[56:57]
	v_pk_mul_f32 v[162:163], v[40:41], s[56:57]
	v_pk_mul_f32 v[164:165], v[42:43], s[56:57]
	v_exp_f32_e32 v158, v158
	v_exp_f32_e32 v159, v159
	v_exp_f32_e32 v160, v160
	v_exp_f32_e32 v161, v161
	v_exp_f32_e32 v162, v162
	v_exp_f32_e32 v163, v163
	v_exp_f32_e32 v164, v164
	v_exp_f32_e32 v165, v165
	v_pk_add_f32 v[158:159], v[158:159], s[58:59]
	v_pk_add_f32 v[160:161], v[160:161], s[58:59]
	v_pk_add_f32 v[162:163], v[162:163], s[58:59]
	v_pk_add_f32 v[164:165], v[164:165], s[58:59]
	v_rcp_f32_e32 v158, v158
	v_rcp_f32_e32 v159, v159
	v_rcp_f32_e32 v160, v160
	v_rcp_f32_e32 v161, v161
	v_rcp_f32_e32 v162, v162
	v_rcp_f32_e32 v163, v163
	v_rcp_f32_e32 v164, v164
	v_rcp_f32_e32 v165, v165
	v_pk_add_f32 v[130:131], s[58:59], v[196:197] neg_lo:[0,1] neg_hi:[0,1]
	v_pk_fma_f32 v[158:159], v[158:159], v[130:131], v[196:197]
	v_pk_add_f32 v[132:133], s[58:59], v[198:199] neg_lo:[0,1] neg_hi:[0,1]
	v_pk_fma_f32 v[160:161], v[160:161], v[132:133], v[198:199]
	v_pk_add_f32 v[130:131], s[58:59], v[134:135] neg_lo:[0,1] neg_hi:[0,1]
	v_pk_fma_f32 v[162:163], v[162:163], v[130:131], v[134:135]
	v_pk_add_f32 v[132:133], s[58:59], v[136:137] neg_lo:[0,1] neg_hi:[0,1]
	v_pk_fma_f32 v[164:165], v[164:165], v[132:133], v[136:137]
	v_log_f32_e32 v158, v158
	v_log_f32_e32 v159, v159
	v_log_f32_e32 v160, v160
	v_log_f32_e32 v161, v161
	v_log_f32_e32 v162, v162
	v_log_f32_e32 v163, v163
	v_log_f32_e32 v164, v164
	v_log_f32_e32 v165, v165
	v_pk_mul_f32 v[44:45], v[158:159], s[2:3]
	v_pk_mul_f32 v[46:47], v[160:161], s[2:3]
	v_pk_mul_f32 v[40:41], v[162:163], s[2:3]
	v_pk_mul_f32 v[42:43], v[164:165], s[2:3]
	v_pk_fma_f32 v[44:45], v[158:159], s[2:3], v[44:45] neg_lo:[0,0,1] neg_hi:[0,0,1]
	v_pk_fma_f32 v[46:47], v[160:161], s[2:3], v[46:47] neg_lo:[0,0,1] neg_hi:[0,0,1]
	v_pk_fma_f32 v[40:41], v[162:163], s[2:3], v[40:41] neg_lo:[0,0,1] neg_hi:[0,0,1]
	v_pk_fma_f32 v[42:43], v[164:165], s[2:3], v[42:43] neg_lo:[0,0,1] neg_hi:[0,0,1]
	v_pk_fma_f32 v[44:45], v[158:159], s[18:19], v[44:45]
	v_pk_fma_f32 v[46:47], v[160:161], s[18:19], v[46:47]
	v_pk_fma_f32 v[40:41], v[162:163], s[18:19], v[40:41]
	v_pk_fma_f32 v[42:43], v[164:165], s[18:19], v[42:43]
	v_pk_fma_f32 v[44:45], v[158:159], s[2:3], v[44:45]
	v_pk_fma_f32 v[46:47], v[160:161], s[2:3], v[46:47]
	v_pk_fma_f32 v[40:41], v[162:163], s[2:3], v[40:41]
	v_pk_fma_f32 v[42:43], v[164:165], s[2:3], v[42:43]
	v_cvt_pk_bf16_f32 v44, v44, v45
	v_cvt_pk_bf16_f32 v45, v46, v47
	v_cvt_pk_bf16_f32 v46, v40, v41
	v_cvt_pk_bf16_f32 v47, v42, v43
	global_store_dwordx4 v157, v[44:47], s[8:9]
	v_add_u32_e32 v157, s20, v157
	v_pk_mul_f32 v[158:159], v[28:29], s[56:57]
	v_pk_mul_f32 v[160:161], v[30:31], s[56:57]
	v_pk_mul_f32 v[162:163], v[24:25], s[56:57]
	v_pk_mul_f32 v[164:165], v[26:27], s[56:57]
	v_exp_f32_e32 v158, v158
	v_exp_f32_e32 v159, v159
	v_exp_f32_e32 v160, v160
	v_exp_f32_e32 v161, v161
	v_exp_f32_e32 v162, v162
	v_exp_f32_e32 v163, v163
	v_exp_f32_e32 v164, v164
	v_exp_f32_e32 v165, v165
	v_pk_add_f32 v[158:159], v[158:159], s[58:59]
	v_pk_add_f32 v[160:161], v[160:161], s[58:59]
	v_pk_add_f32 v[162:163], v[162:163], s[58:59]
	v_pk_add_f32 v[164:165], v[164:165], s[58:59]
	v_rcp_f32_e32 v158, v158
	v_rcp_f32_e32 v159, v159
	v_rcp_f32_e32 v160, v160
	v_rcp_f32_e32 v161, v161
	v_rcp_f32_e32 v162, v162
	v_rcp_f32_e32 v163, v163
	v_rcp_f32_e32 v164, v164
	v_rcp_f32_e32 v165, v165
	v_pk_add_f32 v[130:131], s[58:59], v[196:197] neg_lo:[0,1] neg_hi:[0,1]
	v_pk_fma_f32 v[158:159], v[158:159], v[130:131], v[196:197]
	v_pk_add_f32 v[132:133], s[58:59], v[198:199] neg_lo:[0,1] neg_hi:[0,1]
	v_pk_fma_f32 v[160:161], v[160:161], v[132:133], v[198:199]
	v_pk_add_f32 v[130:131], s[58:59], v[134:135] neg_lo:[0,1] neg_hi:[0,1]
	v_pk_fma_f32 v[162:163], v[162:163], v[130:131], v[134:135]
	v_pk_add_f32 v[132:133], s[58:59], v[136:137] neg_lo:[0,1] neg_hi:[0,1]
	v_pk_fma_f32 v[164:165], v[164:165], v[132:133], v[136:137]
	v_log_f32_e32 v158, v158
	v_log_f32_e32 v159, v159
	v_log_f32_e32 v160, v160
	v_log_f32_e32 v161, v161
	v_log_f32_e32 v162, v162
	v_log_f32_e32 v163, v163
	v_log_f32_e32 v164, v164
	v_log_f32_e32 v165, v165
	v_pk_mul_f32 v[28:29], v[158:159], s[2:3]
	v_pk_mul_f32 v[30:31], v[160:161], s[2:3]
	v_pk_mul_f32 v[24:25], v[162:163], s[2:3]
	v_pk_mul_f32 v[26:27], v[164:165], s[2:3]
	v_pk_fma_f32 v[28:29], v[158:159], s[2:3], v[28:29] neg_lo:[0,0,1] neg_hi:[0,0,1]
	v_pk_fma_f32 v[30:31], v[160:161], s[2:3], v[30:31] neg_lo:[0,0,1] neg_hi:[0,0,1]
	v_pk_fma_f32 v[24:25], v[162:163], s[2:3], v[24:25] neg_lo:[0,0,1] neg_hi:[0,0,1]
	v_pk_fma_f32 v[26:27], v[164:165], s[2:3], v[26:27] neg_lo:[0,0,1] neg_hi:[0,0,1]
	v_pk_fma_f32 v[28:29], v[158:159], s[18:19], v[28:29]
	v_pk_fma_f32 v[30:31], v[160:161], s[18:19], v[30:31]
	v_pk_fma_f32 v[24:25], v[162:163], s[18:19], v[24:25]
	v_pk_fma_f32 v[26:27], v[164:165], s[18:19], v[26:27]
	v_pk_fma_f32 v[28:29], v[158:159], s[2:3], v[28:29]
	v_pk_fma_f32 v[30:31], v[160:161], s[2:3], v[30:31]
	v_pk_fma_f32 v[24:25], v[162:163], s[2:3], v[24:25]
	v_pk_fma_f32 v[26:27], v[164:165], s[2:3], v[26:27]
	v_cvt_pk_bf16_f32 v28, v28, v29
	v_cvt_pk_bf16_f32 v29, v30, v31
	v_cvt_pk_bf16_f32 v30, v24, v25
	v_cvt_pk_bf16_f32 v31, v26, v27
	global_store_dwordx4 v157, v[28:31], s[8:9]
	v_add_u32_e32 v157, s20, v157
	v_pk_mul_f32 v[158:159], v[12:13], s[56:57]
	v_pk_mul_f32 v[160:161], v[14:15], s[56:57]
	v_pk_mul_f32 v[162:163], v[8:9], s[56:57]
	v_pk_mul_f32 v[164:165], v[10:11], s[56:57]
	v_exp_f32_e32 v158, v158
	v_exp_f32_e32 v159, v159
	v_exp_f32_e32 v160, v160
	v_exp_f32_e32 v161, v161
	v_exp_f32_e32 v162, v162
	v_exp_f32_e32 v163, v163
	v_exp_f32_e32 v164, v164
	v_exp_f32_e32 v165, v165
	v_pk_add_f32 v[158:159], v[158:159], s[58:59]
	v_pk_add_f32 v[160:161], v[160:161], s[58:59]
	v_pk_add_f32 v[162:163], v[162:163], s[58:59]
	v_pk_add_f32 v[164:165], v[164:165], s[58:59]
	v_rcp_f32_e32 v158, v158
	v_rcp_f32_e32 v159, v159
	v_rcp_f32_e32 v160, v160
	v_rcp_f32_e32 v161, v161
	v_rcp_f32_e32 v162, v162
	v_rcp_f32_e32 v163, v163
	v_rcp_f32_e32 v164, v164
	v_rcp_f32_e32 v165, v165
	v_pk_add_f32 v[130:131], s[58:59], v[196:197] neg_lo:[0,1] neg_hi:[0,1]
	v_pk_fma_f32 v[158:159], v[158:159], v[130:131], v[196:197]
	v_pk_add_f32 v[132:133], s[58:59], v[198:199] neg_lo:[0,1] neg_hi:[0,1]
	v_pk_fma_f32 v[160:161], v[160:161], v[132:133], v[198:199]
	v_pk_add_f32 v[130:131], s[58:59], v[134:135] neg_lo:[0,1] neg_hi:[0,1]
	v_pk_fma_f32 v[162:163], v[162:163], v[130:131], v[134:135]
	v_pk_add_f32 v[132:133], s[58:59], v[136:137] neg_lo:[0,1] neg_hi:[0,1]
	v_pk_fma_f32 v[164:165], v[164:165], v[132:133], v[136:137]
	v_log_f32_e32 v158, v158
	v_log_f32_e32 v159, v159
	v_log_f32_e32 v160, v160
	v_log_f32_e32 v161, v161
	v_log_f32_e32 v162, v162
	v_log_f32_e32 v163, v163
	v_log_f32_e32 v164, v164
	v_log_f32_e32 v165, v165
	v_pk_mul_f32 v[12:13], v[158:159], s[2:3]
	v_pk_mul_f32 v[14:15], v[160:161], s[2:3]
	v_pk_mul_f32 v[8:9], v[162:163], s[2:3]
	v_pk_mul_f32 v[10:11], v[164:165], s[2:3]
	v_pk_fma_f32 v[12:13], v[158:159], s[2:3], v[12:13] neg_lo:[0,0,1] neg_hi:[0,0,1]
	v_pk_fma_f32 v[14:15], v[160:161], s[2:3], v[14:15] neg_lo:[0,0,1] neg_hi:[0,0,1]
	v_pk_fma_f32 v[8:9], v[162:163], s[2:3], v[8:9] neg_lo:[0,0,1] neg_hi:[0,0,1]
	v_pk_fma_f32 v[10:11], v[164:165], s[2:3], v[10:11] neg_lo:[0,0,1] neg_hi:[0,0,1]
	v_pk_fma_f32 v[12:13], v[158:159], s[18:19], v[12:13]
	v_pk_fma_f32 v[14:15], v[160:161], s[18:19], v[14:15]
	v_pk_fma_f32 v[8:9], v[162:163], s[18:19], v[8:9]
	v_pk_fma_f32 v[10:11], v[164:165], s[18:19], v[10:11]
	v_pk_fma_f32 v[12:13], v[158:159], s[2:3], v[12:13]
	v_pk_fma_f32 v[14:15], v[160:161], s[2:3], v[14:15]
	v_pk_fma_f32 v[8:9], v[162:163], s[2:3], v[8:9]
	v_pk_fma_f32 v[10:11], v[164:165], s[2:3], v[10:11]
	v_cvt_pk_bf16_f32 v12, v12, v13
	v_cvt_pk_bf16_f32 v13, v14, v15
	v_cvt_pk_bf16_f32 v14, v8, v9
	v_cvt_pk_bf16_f32 v15, v10, v11
	global_store_dwordx4 v157, v[12:15], s[8:9]
	v_mov_b32_e32 v157, v167
	s_waitcnt vmcnt(7)
	v_pk_mul_f32 v[158:159], v[118:119], s[56:57]
	v_pk_mul_f32 v[160:161], v[120:121], s[56:57]
	v_pk_mul_f32 v[162:163], v[114:115], s[56:57]
	v_pk_mul_f32 v[164:165], v[116:117], s[56:57]
	v_exp_f32_e32 v158, v158
	v_exp_f32_e32 v159, v159
	v_exp_f32_e32 v160, v160
	v_exp_f32_e32 v161, v161
	v_exp_f32_e32 v162, v162
	v_exp_f32_e32 v163, v163
	v_exp_f32_e32 v164, v164
	v_exp_f32_e32 v165, v165
	v_pk_add_f32 v[158:159], v[158:159], s[58:59]
	v_pk_add_f32 v[160:161], v[160:161], s[58:59]
	v_pk_add_f32 v[162:163], v[162:163], s[58:59]
	v_pk_add_f32 v[164:165], v[164:165], s[58:59]
	v_rcp_f32_e32 v158, v158
	v_rcp_f32_e32 v159, v159
	v_rcp_f32_e32 v160, v160
	v_rcp_f32_e32 v161, v161
	v_rcp_f32_e32 v162, v162
	v_rcp_f32_e32 v163, v163
	v_rcp_f32_e32 v164, v164
	v_rcp_f32_e32 v165, v165
	v_pk_add_f32 v[130:131], s[58:59], v[122:123] neg_lo:[0,1] neg_hi:[0,1]
	v_pk_fma_f32 v[158:159], v[158:159], v[130:131], v[122:123]
	v_pk_add_f32 v[132:133], s[58:59], v[124:125] neg_lo:[0,1] neg_hi:[0,1]
	v_pk_fma_f32 v[160:161], v[160:161], v[132:133], v[124:125]
	v_pk_add_f32 v[130:131], s[58:59], v[126:127] neg_lo:[0,1] neg_hi:[0,1]
	v_pk_fma_f32 v[162:163], v[162:163], v[130:131], v[126:127]
	v_pk_add_f32 v[132:133], s[58:59], v[128:129] neg_lo:[0,1] neg_hi:[0,1]
	v_pk_fma_f32 v[164:165], v[164:165], v[132:133], v[128:129]
	v_log_f32_e32 v158, v158
	v_log_f32_e32 v159, v159
	v_log_f32_e32 v160, v160
	v_log_f32_e32 v161, v161
	v_log_f32_e32 v162, v162
	v_log_f32_e32 v163, v163
	v_log_f32_e32 v164, v164
	v_log_f32_e32 v165, v165
	v_pk_mul_f32 v[118:119], v[158:159], s[2:3]
	v_pk_mul_f32 v[120:121], v[160:161], s[2:3]
	v_pk_mul_f32 v[114:115], v[162:163], s[2:3]
	v_pk_mul_f32 v[116:117], v[164:165], s[2:3]
	v_pk_fma_f32 v[118:119], v[158:159], s[2:3], v[118:119] neg_lo:[0,0,1] neg_hi:[0,0,1]
	v_pk_fma_f32 v[120:121], v[160:161], s[2:3], v[120:121] neg_lo:[0,0,1] neg_hi:[0,0,1]
	v_pk_fma_f32 v[114:115], v[162:163], s[2:3], v[114:115] neg_lo:[0,0,1] neg_hi:[0,0,1]
	v_pk_fma_f32 v[116:117], v[164:165], s[2:3], v[116:117] neg_lo:[0,0,1] neg_hi:[0,0,1]
	v_pk_fma_f32 v[118:119], v[158:159], s[18:19], v[118:119]
	v_pk_fma_f32 v[120:121], v[160:161], s[18:19], v[120:121]
	v_pk_fma_f32 v[114:115], v[162:163], s[18:19], v[114:115]
	v_pk_fma_f32 v[116:117], v[164:165], s[18:19], v[116:117]
	v_pk_fma_f32 v[118:119], v[158:159], s[2:3], v[118:119]
	v_pk_fma_f32 v[120:121], v[160:161], s[2:3], v[120:121]
	v_pk_fma_f32 v[114:115], v[162:163], s[2:3], v[114:115]
	v_pk_fma_f32 v[116:117], v[164:165], s[2:3], v[116:117]
	v_cvt_pk_bf16_f32 v118, v118, v119
	v_cvt_pk_bf16_f32 v119, v120, v121
	v_cvt_pk_bf16_f32 v120, v114, v115
	v_cvt_pk_bf16_f32 v121, v116, v117
	global_store_dwordx4 v157, v[118:121], s[8:9] offset:256
	v_add_u32_e32 v157, s20, v157
	v_pk_mul_f32 v[158:159], v[102:103], s[56:57]
	v_pk_mul_f32 v[160:161], v[104:105], s[56:57]
	v_pk_mul_f32 v[162:163], v[98:99], s[56:57]
	v_pk_mul_f32 v[164:165], v[100:101], s[56:57]
	v_exp_f32_e32 v158, v158
	v_exp_f32_e32 v159, v159
	v_exp_f32_e32 v160, v160
	v_exp_f32_e32 v161, v161
	v_exp_f32_e32 v162, v162
	v_exp_f32_e32 v163, v163
	v_exp_f32_e32 v164, v164
	v_exp_f32_e32 v165, v165
	v_pk_add_f32 v[158:159], v[158:159], s[58:59]
	v_pk_add_f32 v[160:161], v[160:161], s[58:59]
	v_pk_add_f32 v[162:163], v[162:163], s[58:59]
	v_pk_add_f32 v[164:165], v[164:165], s[58:59]
	v_rcp_f32_e32 v158, v158
	v_rcp_f32_e32 v159, v159
	v_rcp_f32_e32 v160, v160
	v_rcp_f32_e32 v161, v161
	v_rcp_f32_e32 v162, v162
	v_rcp_f32_e32 v163, v163
	v_rcp_f32_e32 v164, v164
	v_rcp_f32_e32 v165, v165
	v_pk_add_f32 v[130:131], s[58:59], v[122:123] neg_lo:[0,1] neg_hi:[0,1]
	v_pk_fma_f32 v[158:159], v[158:159], v[130:131], v[122:123]
	v_pk_add_f32 v[132:133], s[58:59], v[124:125] neg_lo:[0,1] neg_hi:[0,1]
	v_pk_fma_f32 v[160:161], v[160:161], v[132:133], v[124:125]
	v_pk_add_f32 v[130:131], s[58:59], v[126:127] neg_lo:[0,1] neg_hi:[0,1]
	v_pk_fma_f32 v[162:163], v[162:163], v[130:131], v[126:127]
	v_pk_add_f32 v[132:133], s[58:59], v[128:129] neg_lo:[0,1] neg_hi:[0,1]
	v_pk_fma_f32 v[164:165], v[164:165], v[132:133], v[128:129]
	v_log_f32_e32 v158, v158
	v_log_f32_e32 v159, v159
	v_log_f32_e32 v160, v160
	v_log_f32_e32 v161, v161
	v_log_f32_e32 v162, v162
	v_log_f32_e32 v163, v163
	v_log_f32_e32 v164, v164
	v_log_f32_e32 v165, v165
	v_pk_mul_f32 v[102:103], v[158:159], s[2:3]
	v_pk_mul_f32 v[104:105], v[160:161], s[2:3]
	v_pk_mul_f32 v[98:99], v[162:163], s[2:3]
	v_pk_mul_f32 v[100:101], v[164:165], s[2:3]
	v_pk_fma_f32 v[102:103], v[158:159], s[2:3], v[102:103] neg_lo:[0,0,1] neg_hi:[0,0,1]
	v_pk_fma_f32 v[104:105], v[160:161], s[2:3], v[104:105] neg_lo:[0,0,1] neg_hi:[0,0,1]
	v_pk_fma_f32 v[98:99], v[162:163], s[2:3], v[98:99] neg_lo:[0,0,1] neg_hi:[0,0,1]
	v_pk_fma_f32 v[100:101], v[164:165], s[2:3], v[100:101] neg_lo:[0,0,1] neg_hi:[0,0,1]
	v_pk_fma_f32 v[102:103], v[158:159], s[18:19], v[102:103]
	v_pk_fma_f32 v[104:105], v[160:161], s[18:19], v[104:105]
	v_pk_fma_f32 v[98:99], v[162:163], s[18:19], v[98:99]
	v_pk_fma_f32 v[100:101], v[164:165], s[18:19], v[100:101]
	v_pk_fma_f32 v[102:103], v[158:159], s[2:3], v[102:103]
	v_pk_fma_f32 v[104:105], v[160:161], s[2:3], v[104:105]
	v_pk_fma_f32 v[98:99], v[162:163], s[2:3], v[98:99]
	v_pk_fma_f32 v[100:101], v[164:165], s[2:3], v[100:101]
	v_cvt_pk_bf16_f32 v102, v102, v103
	v_cvt_pk_bf16_f32 v103, v104, v105
	v_cvt_pk_bf16_f32 v104, v98, v99
	v_cvt_pk_bf16_f32 v105, v100, v101
	global_store_dwordx4 v157, v[102:105], s[8:9] offset:256
	v_add_u32_e32 v157, s20, v157
	v_pk_mul_f32 v[158:159], v[86:87], s[56:57]
	v_pk_mul_f32 v[160:161], v[88:89], s[56:57]
	v_pk_mul_f32 v[162:163], v[82:83], s[56:57]
	v_pk_mul_f32 v[164:165], v[84:85], s[56:57]
	v_exp_f32_e32 v158, v158
	v_exp_f32_e32 v159, v159
	v_exp_f32_e32 v160, v160
	v_exp_f32_e32 v161, v161
	v_exp_f32_e32 v162, v162
	v_exp_f32_e32 v163, v163
	v_exp_f32_e32 v164, v164
	v_exp_f32_e32 v165, v165
	v_pk_add_f32 v[158:159], v[158:159], s[58:59]
	v_pk_add_f32 v[160:161], v[160:161], s[58:59]
	v_pk_add_f32 v[162:163], v[162:163], s[58:59]
	v_pk_add_f32 v[164:165], v[164:165], s[58:59]
	v_rcp_f32_e32 v158, v158
	v_rcp_f32_e32 v159, v159
	v_rcp_f32_e32 v160, v160
	v_rcp_f32_e32 v161, v161
	v_rcp_f32_e32 v162, v162
	v_rcp_f32_e32 v163, v163
	v_rcp_f32_e32 v164, v164
	v_rcp_f32_e32 v165, v165
	v_pk_add_f32 v[130:131], s[58:59], v[122:123] neg_lo:[0,1] neg_hi:[0,1]
	v_pk_fma_f32 v[158:159], v[158:159], v[130:131], v[122:123]
	v_pk_add_f32 v[132:133], s[58:59], v[124:125] neg_lo:[0,1] neg_hi:[0,1]
	v_pk_fma_f32 v[160:161], v[160:161], v[132:133], v[124:125]
	v_pk_add_f32 v[130:131], s[58:59], v[126:127] neg_lo:[0,1] neg_hi:[0,1]
	v_pk_fma_f32 v[162:163], v[162:163], v[130:131], v[126:127]
	v_pk_add_f32 v[132:133], s[58:59], v[128:129] neg_lo:[0,1] neg_hi:[0,1]
	v_pk_fma_f32 v[164:165], v[164:165], v[132:133], v[128:129]
	v_log_f32_e32 v158, v158
	v_log_f32_e32 v159, v159
	v_log_f32_e32 v160, v160
	v_log_f32_e32 v161, v161
	v_log_f32_e32 v162, v162
	v_log_f32_e32 v163, v163
	v_log_f32_e32 v164, v164
	v_log_f32_e32 v165, v165
	v_pk_mul_f32 v[86:87], v[158:159], s[2:3]
	v_pk_mul_f32 v[88:89], v[160:161], s[2:3]
	v_pk_mul_f32 v[82:83], v[162:163], s[2:3]
	v_pk_mul_f32 v[84:85], v[164:165], s[2:3]
	v_pk_fma_f32 v[86:87], v[158:159], s[2:3], v[86:87] neg_lo:[0,0,1] neg_hi:[0,0,1]
	v_pk_fma_f32 v[88:89], v[160:161], s[2:3], v[88:89] neg_lo:[0,0,1] neg_hi:[0,0,1]
	v_pk_fma_f32 v[82:83], v[162:163], s[2:3], v[82:83] neg_lo:[0,0,1] neg_hi:[0,0,1]
	v_pk_fma_f32 v[84:85], v[164:165], s[2:3], v[84:85] neg_lo:[0,0,1] neg_hi:[0,0,1]
	v_pk_fma_f32 v[86:87], v[158:159], s[18:19], v[86:87]
	v_pk_fma_f32 v[88:89], v[160:161], s[18:19], v[88:89]
	v_pk_fma_f32 v[82:83], v[162:163], s[18:19], v[82:83]
	v_pk_fma_f32 v[84:85], v[164:165], s[18:19], v[84:85]
	v_pk_fma_f32 v[86:87], v[158:159], s[2:3], v[86:87]
	v_pk_fma_f32 v[88:89], v[160:161], s[2:3], v[88:89]
	v_pk_fma_f32 v[82:83], v[162:163], s[2:3], v[82:83]
	v_pk_fma_f32 v[84:85], v[164:165], s[2:3], v[84:85]
	v_cvt_pk_bf16_f32 v86, v86, v87
	v_cvt_pk_bf16_f32 v87, v88, v89
	v_cvt_pk_bf16_f32 v88, v82, v83
	v_cvt_pk_bf16_f32 v89, v84, v85
	global_store_dwordx4 v157, v[86:89], s[8:9] offset:256
	v_add_u32_e32 v157, s20, v157
	v_pk_mul_f32 v[158:159], v[70:71], s[56:57]
	v_pk_mul_f32 v[160:161], v[72:73], s[56:57]
	v_pk_mul_f32 v[162:163], v[66:67], s[56:57]
	v_pk_mul_f32 v[164:165], v[68:69], s[56:57]
	v_exp_f32_e32 v158, v158
	v_exp_f32_e32 v159, v159
	v_exp_f32_e32 v160, v160
	v_exp_f32_e32 v161, v161
	v_exp_f32_e32 v162, v162
	v_exp_f32_e32 v163, v163
	v_exp_f32_e32 v164, v164
	v_exp_f32_e32 v165, v165
	v_pk_add_f32 v[158:159], v[158:159], s[58:59]
	v_pk_add_f32 v[160:161], v[160:161], s[58:59]
	v_pk_add_f32 v[162:163], v[162:163], s[58:59]
	v_pk_add_f32 v[164:165], v[164:165], s[58:59]
	v_rcp_f32_e32 v158, v158
	v_rcp_f32_e32 v159, v159
	v_rcp_f32_e32 v160, v160
	v_rcp_f32_e32 v161, v161
	v_rcp_f32_e32 v162, v162
	v_rcp_f32_e32 v163, v163
	v_rcp_f32_e32 v164, v164
	v_rcp_f32_e32 v165, v165
	v_pk_add_f32 v[130:131], s[58:59], v[122:123] neg_lo:[0,1] neg_hi:[0,1]
	v_pk_fma_f32 v[158:159], v[158:159], v[130:131], v[122:123]
	v_pk_add_f32 v[132:133], s[58:59], v[124:125] neg_lo:[0,1] neg_hi:[0,1]
	v_pk_fma_f32 v[160:161], v[160:161], v[132:133], v[124:125]
	v_pk_add_f32 v[130:131], s[58:59], v[126:127] neg_lo:[0,1] neg_hi:[0,1]
	v_pk_fma_f32 v[162:163], v[162:163], v[130:131], v[126:127]
	v_pk_add_f32 v[132:133], s[58:59], v[128:129] neg_lo:[0,1] neg_hi:[0,1]
	v_pk_fma_f32 v[164:165], v[164:165], v[132:133], v[128:129]
	v_log_f32_e32 v158, v158
	v_log_f32_e32 v159, v159
	v_log_f32_e32 v160, v160
	v_log_f32_e32 v161, v161
	v_log_f32_e32 v162, v162
	v_log_f32_e32 v163, v163
	v_log_f32_e32 v164, v164
	v_log_f32_e32 v165, v165
	v_pk_mul_f32 v[70:71], v[158:159], s[2:3]
	v_pk_mul_f32 v[72:73], v[160:161], s[2:3]
	v_pk_mul_f32 v[66:67], v[162:163], s[2:3]
	v_pk_mul_f32 v[68:69], v[164:165], s[2:3]
	v_pk_fma_f32 v[70:71], v[158:159], s[2:3], v[70:71] neg_lo:[0,0,1] neg_hi:[0,0,1]
	v_pk_fma_f32 v[72:73], v[160:161], s[2:3], v[72:73] neg_lo:[0,0,1] neg_hi:[0,0,1]
	v_pk_fma_f32 v[66:67], v[162:163], s[2:3], v[66:67] neg_lo:[0,0,1] neg_hi:[0,0,1]
	v_pk_fma_f32 v[68:69], v[164:165], s[2:3], v[68:69] neg_lo:[0,0,1] neg_hi:[0,0,1]
	v_pk_fma_f32 v[70:71], v[158:159], s[18:19], v[70:71]
	v_pk_fma_f32 v[72:73], v[160:161], s[18:19], v[72:73]
	v_pk_fma_f32 v[66:67], v[162:163], s[18:19], v[66:67]
	v_pk_fma_f32 v[68:69], v[164:165], s[18:19], v[68:69]
	v_pk_fma_f32 v[70:71], v[158:159], s[2:3], v[70:71]
	v_pk_fma_f32 v[72:73], v[160:161], s[2:3], v[72:73]
	v_pk_fma_f32 v[66:67], v[162:163], s[2:3], v[66:67]
	v_pk_fma_f32 v[68:69], v[164:165], s[2:3], v[68:69]
	v_cvt_pk_bf16_f32 v70, v70, v71
	v_cvt_pk_bf16_f32 v71, v72, v73
	v_cvt_pk_bf16_f32 v72, v66, v67
	v_cvt_pk_bf16_f32 v73, v68, v69
	global_store_dwordx4 v157, v[70:73], s[8:9] offset:256
	v_add_u32_e32 v157, s36, v157
	v_pk_mul_f32 v[158:159], v[52:53], s[56:57]
	v_pk_mul_f32 v[160:161], v[54:55], s[56:57]
	v_pk_mul_f32 v[162:163], v[48:49], s[56:57]
	v_pk_mul_f32 v[164:165], v[50:51], s[56:57]
	v_exp_f32_e32 v158, v158
	v_exp_f32_e32 v159, v159
	v_exp_f32_e32 v160, v160
	v_exp_f32_e32 v161, v161
	v_exp_f32_e32 v162, v162
	v_exp_f32_e32 v163, v163
	v_exp_f32_e32 v164, v164
	v_exp_f32_e32 v165, v165
	v_pk_add_f32 v[158:159], v[158:159], s[58:59]
	v_pk_add_f32 v[160:161], v[160:161], s[58:59]
	v_pk_add_f32 v[162:163], v[162:163], s[58:59]
	v_pk_add_f32 v[164:165], v[164:165], s[58:59]
	v_rcp_f32_e32 v158, v158
	v_rcp_f32_e32 v159, v159
	v_rcp_f32_e32 v160, v160
	v_rcp_f32_e32 v161, v161
	v_rcp_f32_e32 v162, v162
	v_rcp_f32_e32 v163, v163
	v_rcp_f32_e32 v164, v164
	v_rcp_f32_e32 v165, v165
	v_pk_add_f32 v[130:131], s[58:59], v[122:123] neg_lo:[0,1] neg_hi:[0,1]
	v_pk_fma_f32 v[158:159], v[158:159], v[130:131], v[122:123]
	v_pk_add_f32 v[132:133], s[58:59], v[124:125] neg_lo:[0,1] neg_hi:[0,1]
	v_pk_fma_f32 v[160:161], v[160:161], v[132:133], v[124:125]
	v_pk_add_f32 v[130:131], s[58:59], v[126:127] neg_lo:[0,1] neg_hi:[0,1]
	v_pk_fma_f32 v[162:163], v[162:163], v[130:131], v[126:127]
	v_pk_add_f32 v[132:133], s[58:59], v[128:129] neg_lo:[0,1] neg_hi:[0,1]
	v_pk_fma_f32 v[164:165], v[164:165], v[132:133], v[128:129]
	v_log_f32_e32 v158, v158
	v_log_f32_e32 v159, v159
	v_log_f32_e32 v160, v160
	v_log_f32_e32 v161, v161
	v_log_f32_e32 v162, v162
	v_log_f32_e32 v163, v163
	v_log_f32_e32 v164, v164
	v_log_f32_e32 v165, v165
	v_pk_mul_f32 v[52:53], v[158:159], s[2:3]
	v_pk_mul_f32 v[54:55], v[160:161], s[2:3]
	v_pk_mul_f32 v[48:49], v[162:163], s[2:3]
	v_pk_mul_f32 v[50:51], v[164:165], s[2:3]
	v_pk_fma_f32 v[52:53], v[158:159], s[2:3], v[52:53] neg_lo:[0,0,1] neg_hi:[0,0,1]
	v_pk_fma_f32 v[54:55], v[160:161], s[2:3], v[54:55] neg_lo:[0,0,1] neg_hi:[0,0,1]
	v_pk_fma_f32 v[48:49], v[162:163], s[2:3], v[48:49] neg_lo:[0,0,1] neg_hi:[0,0,1]
	v_pk_fma_f32 v[50:51], v[164:165], s[2:3], v[50:51] neg_lo:[0,0,1] neg_hi:[0,0,1]
	v_pk_fma_f32 v[52:53], v[158:159], s[18:19], v[52:53]
	v_pk_fma_f32 v[54:55], v[160:161], s[18:19], v[54:55]
	v_pk_fma_f32 v[48:49], v[162:163], s[18:19], v[48:49]
	v_pk_fma_f32 v[50:51], v[164:165], s[18:19], v[50:51]
	v_pk_fma_f32 v[52:53], v[158:159], s[2:3], v[52:53]
	v_pk_fma_f32 v[54:55], v[160:161], s[2:3], v[54:55]
	v_pk_fma_f32 v[48:49], v[162:163], s[2:3], v[48:49]
	v_pk_fma_f32 v[50:51], v[164:165], s[2:3], v[50:51]
	v_cvt_pk_bf16_f32 v52, v52, v53
	v_cvt_pk_bf16_f32 v53, v54, v55
	v_cvt_pk_bf16_f32 v54, v48, v49
	v_cvt_pk_bf16_f32 v55, v50, v51
	global_store_dwordx4 v157, v[52:55], s[8:9] offset:256
	v_add_u32_e32 v157, s20, v157
	v_pk_mul_f32 v[158:159], v[36:37], s[56:57]
	v_pk_mul_f32 v[160:161], v[38:39], s[56:57]
	v_pk_mul_f32 v[162:163], v[32:33], s[56:57]
	v_pk_mul_f32 v[164:165], v[34:35], s[56:57]
	v_exp_f32_e32 v158, v158
	v_exp_f32_e32 v159, v159
	v_exp_f32_e32 v160, v160
	v_exp_f32_e32 v161, v161
	v_exp_f32_e32 v162, v162
	v_exp_f32_e32 v163, v163
	v_exp_f32_e32 v164, v164
	v_exp_f32_e32 v165, v165
	v_pk_add_f32 v[158:159], v[158:159], s[58:59]
	v_pk_add_f32 v[160:161], v[160:161], s[58:59]
	v_pk_add_f32 v[162:163], v[162:163], s[58:59]
	v_pk_add_f32 v[164:165], v[164:165], s[58:59]
	v_rcp_f32_e32 v158, v158
	v_rcp_f32_e32 v159, v159
	v_rcp_f32_e32 v160, v160
	v_rcp_f32_e32 v161, v161
	v_rcp_f32_e32 v162, v162
	v_rcp_f32_e32 v163, v163
	v_rcp_f32_e32 v164, v164
	v_rcp_f32_e32 v165, v165
	v_pk_add_f32 v[130:131], s[58:59], v[122:123] neg_lo:[0,1] neg_hi:[0,1]
	v_pk_fma_f32 v[158:159], v[158:159], v[130:131], v[122:123]
	v_pk_add_f32 v[132:133], s[58:59], v[124:125] neg_lo:[0,1] neg_hi:[0,1]
	v_pk_fma_f32 v[160:161], v[160:161], v[132:133], v[124:125]
	v_pk_add_f32 v[130:131], s[58:59], v[126:127] neg_lo:[0,1] neg_hi:[0,1]
	v_pk_fma_f32 v[162:163], v[162:163], v[130:131], v[126:127]
	v_pk_add_f32 v[132:133], s[58:59], v[128:129] neg_lo:[0,1] neg_hi:[0,1]
	v_pk_fma_f32 v[164:165], v[164:165], v[132:133], v[128:129]
	v_log_f32_e32 v158, v158
	v_log_f32_e32 v159, v159
	v_log_f32_e32 v160, v160
	v_log_f32_e32 v161, v161
	v_log_f32_e32 v162, v162
	v_log_f32_e32 v163, v163
	v_log_f32_e32 v164, v164
	v_log_f32_e32 v165, v165
	v_pk_mul_f32 v[36:37], v[158:159], s[2:3]
	v_pk_mul_f32 v[38:39], v[160:161], s[2:3]
	v_pk_mul_f32 v[32:33], v[162:163], s[2:3]
	v_pk_mul_f32 v[34:35], v[164:165], s[2:3]
	v_pk_fma_f32 v[36:37], v[158:159], s[2:3], v[36:37] neg_lo:[0,0,1] neg_hi:[0,0,1]
	v_pk_fma_f32 v[38:39], v[160:161], s[2:3], v[38:39] neg_lo:[0,0,1] neg_hi:[0,0,1]
	v_pk_fma_f32 v[32:33], v[162:163], s[2:3], v[32:33] neg_lo:[0,0,1] neg_hi:[0,0,1]
	v_pk_fma_f32 v[34:35], v[164:165], s[2:3], v[34:35] neg_lo:[0,0,1] neg_hi:[0,0,1]
	v_pk_fma_f32 v[36:37], v[158:159], s[18:19], v[36:37]
	v_pk_fma_f32 v[38:39], v[160:161], s[18:19], v[38:39]
	v_pk_fma_f32 v[32:33], v[162:163], s[18:19], v[32:33]
	v_pk_fma_f32 v[34:35], v[164:165], s[18:19], v[34:35]
	v_pk_fma_f32 v[36:37], v[158:159], s[2:3], v[36:37]
	v_pk_fma_f32 v[38:39], v[160:161], s[2:3], v[38:39]
	v_pk_fma_f32 v[32:33], v[162:163], s[2:3], v[32:33]
	v_pk_fma_f32 v[34:35], v[164:165], s[2:3], v[34:35]
	v_cvt_pk_bf16_f32 v36, v36, v37
	v_cvt_pk_bf16_f32 v37, v38, v39
	v_cvt_pk_bf16_f32 v38, v32, v33
	v_cvt_pk_bf16_f32 v39, v34, v35
	global_store_dwordx4 v157, v[36:39], s[8:9] offset:256
	v_add_u32_e32 v157, s20, v157
	v_pk_mul_f32 v[158:159], v[20:21], s[56:57]
	v_pk_mul_f32 v[160:161], v[22:23], s[56:57]
	v_pk_mul_f32 v[162:163], v[16:17], s[56:57]
	v_pk_mul_f32 v[164:165], v[18:19], s[56:57]
	v_exp_f32_e32 v158, v158
	v_exp_f32_e32 v159, v159
	v_exp_f32_e32 v160, v160
	v_exp_f32_e32 v161, v161
	v_exp_f32_e32 v162, v162
	v_exp_f32_e32 v163, v163
	v_exp_f32_e32 v164, v164
	v_exp_f32_e32 v165, v165
	v_pk_add_f32 v[158:159], v[158:159], s[58:59]
	v_pk_add_f32 v[160:161], v[160:161], s[58:59]
	v_pk_add_f32 v[162:163], v[162:163], s[58:59]
	v_pk_add_f32 v[164:165], v[164:165], s[58:59]
	v_rcp_f32_e32 v158, v158
	v_rcp_f32_e32 v159, v159
	v_rcp_f32_e32 v160, v160
	v_rcp_f32_e32 v161, v161
	v_rcp_f32_e32 v162, v162
	v_rcp_f32_e32 v163, v163
	v_rcp_f32_e32 v164, v164
	v_rcp_f32_e32 v165, v165
	v_pk_add_f32 v[130:131], s[58:59], v[122:123] neg_lo:[0,1] neg_hi:[0,1]
	v_pk_fma_f32 v[158:159], v[158:159], v[130:131], v[122:123]
	v_pk_add_f32 v[132:133], s[58:59], v[124:125] neg_lo:[0,1] neg_hi:[0,1]
	v_pk_fma_f32 v[160:161], v[160:161], v[132:133], v[124:125]
	v_pk_add_f32 v[130:131], s[58:59], v[126:127] neg_lo:[0,1] neg_hi:[0,1]
	v_pk_fma_f32 v[162:163], v[162:163], v[130:131], v[126:127]
	v_pk_add_f32 v[132:133], s[58:59], v[128:129] neg_lo:[0,1] neg_hi:[0,1]
	v_pk_fma_f32 v[164:165], v[164:165], v[132:133], v[128:129]
	v_log_f32_e32 v158, v158
	v_log_f32_e32 v159, v159
	v_log_f32_e32 v160, v160
	v_log_f32_e32 v161, v161
	v_log_f32_e32 v162, v162
	v_log_f32_e32 v163, v163
	v_log_f32_e32 v164, v164
	v_log_f32_e32 v165, v165
	v_pk_mul_f32 v[20:21], v[158:159], s[2:3]
	v_pk_mul_f32 v[22:23], v[160:161], s[2:3]
	v_pk_mul_f32 v[16:17], v[162:163], s[2:3]
	v_pk_mul_f32 v[18:19], v[164:165], s[2:3]
	v_pk_fma_f32 v[20:21], v[158:159], s[2:3], v[20:21] neg_lo:[0,0,1] neg_hi:[0,0,1]
	v_pk_fma_f32 v[22:23], v[160:161], s[2:3], v[22:23] neg_lo:[0,0,1] neg_hi:[0,0,1]
	v_pk_fma_f32 v[16:17], v[162:163], s[2:3], v[16:17] neg_lo:[0,0,1] neg_hi:[0,0,1]
	v_pk_fma_f32 v[18:19], v[164:165], s[2:3], v[18:19] neg_lo:[0,0,1] neg_hi:[0,0,1]
	v_pk_fma_f32 v[20:21], v[158:159], s[18:19], v[20:21]
	v_pk_fma_f32 v[22:23], v[160:161], s[18:19], v[22:23]
	v_pk_fma_f32 v[16:17], v[162:163], s[18:19], v[16:17]
	v_pk_fma_f32 v[18:19], v[164:165], s[18:19], v[18:19]
	v_pk_fma_f32 v[20:21], v[158:159], s[2:3], v[20:21]
	v_pk_fma_f32 v[22:23], v[160:161], s[2:3], v[22:23]
	v_pk_fma_f32 v[16:17], v[162:163], s[2:3], v[16:17]
	v_pk_fma_f32 v[18:19], v[164:165], s[2:3], v[18:19]
	v_cvt_pk_bf16_f32 v20, v20, v21
	v_cvt_pk_bf16_f32 v21, v22, v23
	v_cvt_pk_bf16_f32 v22, v16, v17
	v_cvt_pk_bf16_f32 v23, v18, v19
	global_store_dwordx4 v157, v[20:23], s[8:9] offset:256
	v_add_u32_e32 v157, s20, v157
	v_pk_mul_f32 v[158:159], v[4:5], s[56:57]
	v_pk_mul_f32 v[160:161], v[6:7], s[56:57]
	v_pk_mul_f32 v[162:163], v[0:1], s[56:57]
	v_pk_mul_f32 v[164:165], v[2:3], s[56:57]
	v_exp_f32_e32 v158, v158
	v_exp_f32_e32 v159, v159
	v_exp_f32_e32 v160, v160
	v_exp_f32_e32 v161, v161
	v_exp_f32_e32 v162, v162
	v_exp_f32_e32 v163, v163
	v_exp_f32_e32 v164, v164
	v_exp_f32_e32 v165, v165
	v_pk_add_f32 v[158:159], v[158:159], s[58:59]
	v_pk_add_f32 v[160:161], v[160:161], s[58:59]
	v_pk_add_f32 v[162:163], v[162:163], s[58:59]
	v_pk_add_f32 v[164:165], v[164:165], s[58:59]
	v_rcp_f32_e32 v158, v158
	v_rcp_f32_e32 v159, v159
	v_rcp_f32_e32 v160, v160
	v_rcp_f32_e32 v161, v161
	v_rcp_f32_e32 v162, v162
	v_rcp_f32_e32 v163, v163
	v_rcp_f32_e32 v164, v164
	v_rcp_f32_e32 v165, v165
	v_pk_add_f32 v[130:131], s[58:59], v[122:123] neg_lo:[0,1] neg_hi:[0,1]
	v_pk_fma_f32 v[158:159], v[158:159], v[130:131], v[122:123]
	v_pk_add_f32 v[132:133], s[58:59], v[124:125] neg_lo:[0,1] neg_hi:[0,1]
	v_pk_fma_f32 v[160:161], v[160:161], v[132:133], v[124:125]
	v_pk_add_f32 v[130:131], s[58:59], v[126:127] neg_lo:[0,1] neg_hi:[0,1]
	v_pk_fma_f32 v[162:163], v[162:163], v[130:131], v[126:127]
	v_pk_add_f32 v[132:133], s[58:59], v[128:129] neg_lo:[0,1] neg_hi:[0,1]
	v_pk_fma_f32 v[164:165], v[164:165], v[132:133], v[128:129]
	v_log_f32_e32 v158, v158
	v_log_f32_e32 v159, v159
	v_log_f32_e32 v160, v160
	v_log_f32_e32 v161, v161
	v_log_f32_e32 v162, v162
	v_log_f32_e32 v163, v163
	v_log_f32_e32 v164, v164
	v_log_f32_e32 v165, v165
	v_pk_mul_f32 v[4:5], v[158:159], s[2:3]
	v_pk_mul_f32 v[6:7], v[160:161], s[2:3]
	v_pk_mul_f32 v[0:1], v[162:163], s[2:3]
	v_pk_mul_f32 v[2:3], v[164:165], s[2:3]
	v_pk_fma_f32 v[4:5], v[158:159], s[2:3], v[4:5] neg_lo:[0,0,1] neg_hi:[0,0,1]
	v_pk_fma_f32 v[6:7], v[160:161], s[2:3], v[6:7] neg_lo:[0,0,1] neg_hi:[0,0,1]
	v_pk_fma_f32 v[0:1], v[162:163], s[2:3], v[0:1] neg_lo:[0,0,1] neg_hi:[0,0,1]
	v_pk_fma_f32 v[2:3], v[164:165], s[2:3], v[2:3] neg_lo:[0,0,1] neg_hi:[0,0,1]
	v_pk_fma_f32 v[4:5], v[158:159], s[18:19], v[4:5]
	v_pk_fma_f32 v[6:7], v[160:161], s[18:19], v[6:7]
	v_pk_fma_f32 v[0:1], v[162:163], s[18:19], v[0:1]
	v_pk_fma_f32 v[2:3], v[164:165], s[18:19], v[2:3]
	v_pk_fma_f32 v[4:5], v[158:159], s[2:3], v[4:5]
	v_pk_fma_f32 v[6:7], v[160:161], s[2:3], v[6:7]
	v_pk_fma_f32 v[0:1], v[162:163], s[2:3], v[0:1]
	v_pk_fma_f32 v[2:3], v[164:165], s[2:3], v[2:3]
	v_cvt_pk_bf16_f32 v4, v4, v5
	v_cvt_pk_bf16_f32 v5, v6, v7
	v_cvt_pk_bf16_f32 v6, v0, v1
	v_cvt_pk_bf16_f32 v7, v2, v3
	global_store_dwordx4 v157, v[4:7], s[8:9] offset:256
	s_branch .Lepi_exit
.Lepi_copy:
	v_cvt_pk_bf16_f32 v126, v126, v127
	v_cvt_pk_bf16_f32 v127, v128, v129
	v_cvt_pk_bf16_f32 v128, v122, v123
	v_cvt_pk_bf16_f32 v129, v124, v125
	global_store_dwordx4 v157, v[126:129], s[8:9]
	v_cvt_pk_bf16_f32 v118, v118, v119
	v_cvt_pk_bf16_f32 v119, v120, v121
	v_cvt_pk_bf16_f32 v120, v114, v115
	v_cvt_pk_bf16_f32 v121, v116, v117
	global_store_dwordx4 v157, v[118:121], s[8:9] offset:256
	v_add_u32_e32 v157, s20, v157
	v_cvt_pk_bf16_f32 v110, v110, v111
	v_cvt_pk_bf16_f32 v111, v112, v113
	v_cvt_pk_bf16_f32 v112, v106, v107
	v_cvt_pk_bf16_f32 v113, v108, v109
	global_store_dwordx4 v157, v[110:113], s[8:9]
	v_cvt_pk_bf16_f32 v102, v102, v103
	v_cvt_pk_bf16_f32 v103, v104, v105
	v_cvt_pk_bf16_f32 v104, v98, v99
	v_cvt_pk_bf16_f32 v105, v100, v101
	global_store_dwordx4 v157, v[102:105], s[8:9] offset:256
	v_add_u32_e32 v157, s20, v157
	v_cvt_pk_bf16_f32 v94, v94, v95
	v_cvt_pk_bf16_f32 v95, v96, v97
	v_cvt_pk_bf16_f32 v96, v90, v91
	v_cvt_pk_bf16_f32 v97, v92, v93
	global_store_dwordx4 v157, v[94:97], s[8:9]
	v_cvt_pk_bf16_f32 v86, v86, v87
	v_cvt_pk_bf16_f32 v87, v88, v89
	v_cvt_pk_bf16_f32 v88, v82, v83
	v_cvt_pk_bf16_f32 v89, v84, v85
	global_store_dwordx4 v157, v[86:89], s[8:9] offset:256
	v_add_u32_e32 v157, s20, v157
	v_cvt_pk_bf16_f32 v78, v78, v79
	v_cvt_pk_bf16_f32 v79, v80, v81
	v_cvt_pk_bf16_f32 v80, v74, v75
	v_cvt_pk_bf16_f32 v81, v76, v77
	global_store_dwordx4 v157, v[78:81], s[8:9]
	v_cvt_pk_bf16_f32 v70, v70, v71
	v_cvt_pk_bf16_f32 v71, v72, v73
	v_cvt_pk_bf16_f32 v72, v66, v67
	v_cvt_pk_bf16_f32 v73, v68, v69
	global_store_dwordx4 v157, v[70:73], s[8:9] offset:256
	v_add_u32_e32 v157, s36, v157
	v_cvt_pk_bf16_f32 v60, v60, v61
	v_cvt_pk_bf16_f32 v61, v62, v63
	v_cvt_pk_bf16_f32 v62, v56, v57
	v_cvt_pk_bf16_f32 v63, v58, v59
	global_store_dwordx4 v157, v[60:63], s[8:9]
	v_cvt_pk_bf16_f32 v52, v52, v53
	v_cvt_pk_bf16_f32 v53, v54, v55
	v_cvt_pk_bf16_f32 v54, v48, v49
	v_cvt_pk_bf16_f32 v55, v50, v51
	global_store_dwordx4 v157, v[52:55], s[8:9] offset:256
	v_add_u32_e32 v157, s20, v157
	v_cvt_pk_bf16_f32 v44, v44, v45
	v_cvt_pk_bf16_f32 v45, v46, v47
	v_cvt_pk_bf16_f32 v46, v40, v41
	v_cvt_pk_bf16_f32 v47, v42, v43
	global_store_dwordx4 v157, v[44:47], s[8:9]
	v_cvt_pk_bf16_f32 v36, v36, v37
	v_cvt_pk_bf16_f32 v37, v38, v39
	v_cvt_pk_bf16_f32 v38, v32, v33
	v_cvt_pk_bf16_f32 v39, v34, v35
	global_store_dwordx4 v157, v[36:39], s[8:9] offset:256
	v_add_u32_e32 v157, s20, v157
	v_cvt_pk_bf16_f32 v28, v28, v29
	v_cvt_pk_bf16_f32 v29, v30, v31
	v_cvt_pk_bf16_f32 v30, v24, v25
	v_cvt_pk_bf16_f32 v31, v26, v27
	global_store_dwordx4 v157, v[28:31], s[8:9]
	v_cvt_pk_bf16_f32 v20, v20, v21
	v_cvt_pk_bf16_f32 v21, v22, v23
	v_cvt_pk_bf16_f32 v22, v16, v17
	v_cvt_pk_bf16_f32 v23, v18, v19
	global_store_dwordx4 v157, v[20:23], s[8:9] offset:256
	v_add_u32_e32 v157, s20, v157
	v_cvt_pk_bf16_f32 v12, v12, v13
	v_cvt_pk_bf16_f32 v13, v14, v15
	v_cvt_pk_bf16_f32 v14, v8, v9
	v_cvt_pk_bf16_f32 v15, v10, v11
	global_store_dwordx4 v157, v[12:15], s[8:9]
	v_cvt_pk_bf16_f32 v4, v4, v5
	v_cvt_pk_bf16_f32 v5, v6, v7
	v_cvt_pk_bf16_f32 v6, v0, v1
	v_cvt_pk_bf16_f32 v7, v2, v3
	global_store_dwordx4 v157, v[4:7], s[8:9] offset:256
.Lepi_exit:
	s_andn2_b64 vcc, exec, s[38:39]
	s_mov_b64 s[0:1], -1
	s_branch .Lepi_done

.Lepi_done:
	s_cbranch_vccnz .LBB0_577
	s_andn2_b64 vcc, exec, s[66:67]
	s_cbranch_vccnz .LBB0_576
	s_barrier
	s_branch .LBB0_576

	.amdhsa_kernel _Z10fwd_kernel4Args
		.amdhsa_group_segment_fixed_size 16384
		.amdhsa_private_segment_fixed_size 0
		.amdhsa_kernarg_size 440
		.amdhsa_user_sgpr_count 2
		.amdhsa_user_sgpr_dispatch_ptr 0
		.amdhsa_user_sgpr_queue_ptr 0
		.amdhsa_user_sgpr_kernarg_segment_ptr 1
		.amdhsa_user_sgpr_dispatch_id 0
		.amdhsa_user_sgpr_kernarg_preload_length 0
		.amdhsa_user_sgpr_kernarg_preload_offset 0
		.amdhsa_user_sgpr_private_segment_size 0
		.amdhsa_uses_dynamic_stack 0
		.amdhsa_enable_private_segment 0
		.amdhsa_system_sgpr_workgroup_id_x 1
		.amdhsa_system_sgpr_workgroup_id_y 0
		.amdhsa_system_sgpr_workgroup_id_z 0
		.amdhsa_system_sgpr_workgroup_info 0
		.amdhsa_system_vgpr_workitem_id 2
		.amdhsa_next_free_vgpr 256
		.amdhsa_next_free_sgpr 102
		.amdhsa_accum_offset 256
		.amdhsa_reserve_vcc 1
		.amdhsa_float_round_mode_32 0
		.amdhsa_float_round_mode_16_64 0
		.amdhsa_float_denorm_mode_32 3
		.amdhsa_float_denorm_mode_16_64 3
		.amdhsa_dx10_clamp 1
		.amdhsa_ieee_mode 1
		.amdhsa_fp16_overflow 0
		.amdhsa_tg_split 0
		.amdhsa_exception_fp_ieee_invalid_op 0
		.amdhsa_exception_fp_denorm_src 0
		.amdhsa_exception_fp_ieee_div_zero 0
		.amdhsa_exception_fp_ieee_overflow 0
		.amdhsa_exception_fp_ieee_underflow 0
		.amdhsa_exception_fp_ieee_inexact 0
		.amdhsa_exception_int_div_zero 0
	.end_amdhsa_kernel

amdhsa.kernels:
  - .agpr_count:     0
    .args:
      - .offset:         0
        .size:           184
        .value_kind:     by_value
      - .offset:         184
        .size:           4
        .value_kind:     hidden_block_count_x
      - .offset:         188
        .size:           4
        .value_kind:     hidden_block_count_y
      - .offset:         192
        .size:           4
        .value_kind:     hidden_block_count_z
      - .offset:         196
        .size:           2
        .value_kind:     hidden_group_size_x
      - .offset:         198
        .size:           2
        .value_kind:     hidden_group_size_y
      - .offset:         200
        .size:           2
        .value_kind:     hidden_group_size_z
      - .offset:         202
        .size:           2
        .value_kind:     hidden_remainder_x
      - .offset:         204
        .size:           2
        .value_kind:     hidden_remainder_y
      - .offset:         206
        .size:           2
        .value_kind:     hidden_remainder_z
      - .offset:         224
        .size:           8
        .value_kind:     hidden_global_offset_x
      - .offset:         232
        .size:           8
        .value_kind:     hidden_global_offset_y
      - .offset:         240
        .size:           8
        .value_kind:     hidden_global_offset_z
      - .offset:         248
        .size:           2
        .value_kind:     hidden_grid_dims
      - .offset:         272
        .size:           8
        .value_kind:     hidden_multigrid_sync_arg
      - .offset:         304
        .size:           4
        .value_kind:     hidden_dynamic_lds_size
    .group_segment_fixed_size: 16384
    .kernarg_segment_align: 8
    .kernarg_segment_size: 440
    .language:       OpenCL C
    .language_version:
      - 2
      - 0
    .max_flat_workgroup_size: 512
    .name:           _Z10fwd_kernel4Args
    .private_segment_fixed_size: 0
    .sgpr_count:     108
    .sgpr_spill_count: 357
    .symbol:         _Z10fwd_kernel4Args.kd
    .uniform_work_group_size: 1
    .uses_dynamic_stack: false
    .vgpr_count:     256
    .vgpr_spill_count: 0
    .wavefront_size: 64
